# conv phase gelu_tanh argument evaluated as x*(c1+c2*x*x) with folded constants: 3 instead of 5 VALU ops per element (f32)
# speedup vs baseline: 1.0071x; 1.0036x over previous
; __device__ __forceinline__ unsigned cvt_pk_bf16(float lo, float hi) { unsigned r; asm volatile("v_cvt_pk_bf16_f32 %0, %1, %2" : "=v"(r) : "v"(lo), "v"(hi)); return r; }
; __device__ __forceinline__ float gelu_tanh(float x) {
;     const float y = 0.7978845608028654f * (x + 0.044715f * x * x * x);
;     return x * __builtin_amdgcn_rcpf(1.0f + __builtin_amdgcn_exp2f(-2.0f * LOG2E * y));
; }
; __device__ __forceinline__ void phase_conv(const Params& p, int layer) {
;     ...
;         for (int rb = 0; rb < RCH; rb += 8) {
;             u32x4 gr[8], ur[8];
; #pragma unroll
;             for (int k = 0; k < 8; ++k) { gr[k] = __builtin_nontemporal_load((const u32x4*)(U + (size_t)(r0 + rb + k) * DFF2 + c)); ur[k] = __builtin_nontemporal_load((const u32x4*)(U + (size_t)(r0 + rb + k) * DFF2 + DFF + c)); }
; #pragma unroll
;             for (int k = 0; k < 8; ++k) {
;                 float g0[8], u0[8]; unpack8(gr[k], g0); unpack8(ur[k], u0);
;                 float o[8];
; #pragma unroll
;                 for (int e = 0; e < 8; ++e) {
;                     const float gp = bg[e] + wg[0][e] * g2[e] + wg[1][e] * g1[e] + wg[2][e] * g0[e];
;                     const float up = bu[e] + wu[0][e] * u2[e] + wu[1][e] * u1[e] + wu[2][e] * u0[e];
;                     o[e] = gelu_tanh(gp) * up;
;                     g2[e] = g1[e]; g1[e] = g0[e]; u2[e] = u1[e]; u1[e] = u0[e];
;                 }
;                 u32x4 w; w.x = cvt_pk_bf16(o[0], o[1]); w.y = cvt_pk_bf16(o[2], o[3]); w.z = cvt_pk_bf16(o[4], o[5]); w.w = cvt_pk_bf16(o[6], o[7]);
;                 *(u32x4*)(Gd + (size_t)(r0 + rb + k) * DFF + c) = w;
.LBB0_386:
	v_mov_b32_e32 v251, 0xc0135761
	s_or_b64 exec, exec, s[18:19]
	v_mov_b64_e32 v[146:147], s[4:5]
	s_movk_i32 s7, 0x5800
	v_mad_i64_i32 v[34:35], s[2:3], v179, s7, v[146:147]
	v_lshl_add_u64 v[34:35], v[34:35], 0, v[144:145]
	s_movk_i32 s6, 0x2000
	global_load_dwordx4 v[122:125], v[34:35], off nt
	v_add_co_u32_e32 v34, vcc, s6, v34
	s_waitcnt vmcnt(13)
	v_mov_b32_e32 v132, v114
	v_addc_co_u32_e32 v35, vcc, 0, v35, vcc
	global_load_dwordx4 v[126:129], v[34:35], off offset:3072 nt
	v_mov_b32_e32 v133, v18
	s_waitcnt vmcnt(2)
	v_mov_b32_e32 v134, v118
	v_mov_b32_e32 v135, v30
	v_pk_fma_f32 v[138:139], v[132:133], v[136:137], v[134:135]
	v_mov_b32_e32 v136, v106
	v_mov_b32_e32 v137, v22
	v_pk_fma_f32 v[176:177], v[136:137], v[164:165], v[138:139]
	v_mov_b32_e32 v138, v110
	v_mov_b32_e32 v139, v26
	v_mov_b32_e32 v30, v119
	v_mov_b32_e32 v22, v107
	v_mov_b32_e32 v26, v111
	v_mov_b32_e32 v111, v32
	v_mov_b32_e32 v32, v121
	v_or_b32_e32 v186, 1, v179
	v_mad_i64_i32 v[34:35], s[2:3], v186, s7, v[146:147]
	v_lshl_add_u64 v[34:35], v[34:35], 0, v[144:145]
	global_load_dwordx4 v[98:101], v[34:35], off nt
	v_add_co_u32_e32 v34, vcc, s6, v34
	v_or_b32_e32 v185, 2, v179
	s_nop 0
	v_addc_co_u32_e32 v35, vcc, 0, v35, vcc
	global_load_dwordx4 v[102:105], v[34:35], off offset:3072 nt
	v_mad_i64_i32 v[34:35], s[2:3], v185, s7, v[146:147]
	v_lshl_add_u64 v[34:35], v[34:35], 0, v[144:145]
	global_load_dwordx4 v[74:77], v[34:35], off nt
	v_add_co_u32_e32 v34, vcc, s6, v34
	v_or_b32_e32 v184, 3, v179
	s_nop 0
	v_addc_co_u32_e32 v35, vcc, 0, v35, vcc
	global_load_dwordx4 v[78:81], v[34:35], off offset:3072 nt
	v_mad_i64_i32 v[34:35], s[2:3], v184, s7, v[146:147]
	v_lshl_add_u64 v[34:35], v[34:35], 0, v[144:145]
	global_load_dwordx4 v[66:69], v[34:35], off nt
	v_add_co_u32_e32 v34, vcc, s6, v34
	v_or_b32_e32 v183, 4, v179
	s_nop 0
	v_addc_co_u32_e32 v35, vcc, 0, v35, vcc
	global_load_dwordx4 v[70:73], v[34:35], off offset:3072 nt
	v_mad_i64_i32 v[34:35], s[2:3], v183, s7, v[146:147]
	v_lshl_add_u64 v[34:35], v[34:35], 0, v[144:145]
	global_load_dwordx4 v[58:61], v[34:35], off nt
	v_add_co_u32_e32 v34, vcc, s6, v34
	v_or_b32_e32 v182, 5, v179
	s_nop 0
	v_addc_co_u32_e32 v35, vcc, 0, v35, vcc
	global_load_dwordx4 v[62:65], v[34:35], off offset:3072 nt
	v_mad_i64_i32 v[34:35], s[2:3], v182, s7, v[146:147]
	v_lshl_add_u64 v[34:35], v[34:35], 0, v[144:145]
	global_load_dwordx4 v[50:53], v[34:35], off nt
	v_add_co_u32_e32 v34, vcc, s6, v34
	v_or_b32_e32 v181, 6, v179
	s_nop 0
	v_addc_co_u32_e32 v35, vcc, 0, v35, vcc
	global_load_dwordx4 v[54:57], v[34:35], off offset:3072 nt
	v_mad_i64_i32 v[34:35], s[2:3], v181, s7, v[146:147]
	v_lshl_add_u64 v[34:35], v[34:35], 0, v[144:145]
	global_load_dwordx4 v[42:45], v[34:35], off nt
	v_add_co_u32_e32 v34, vcc, s6, v34
	v_or_b32_e32 v180, 7, v179
	s_nop 0
	v_addc_co_u32_e32 v35, vcc, 0, v35, vcc
	s_waitcnt vmcnt(12)
	v_lshlrev_b32_e32 v171, 16, v122
	global_load_dwordx4 v[46:49], v[34:35], off offset:3072 nt
	v_mad_i64_i32 v[34:35], s[2:3], v180, s7, v[146:147]
	v_lshl_add_u64 v[38:39], v[34:35], 0, v[144:145]
	s_waitcnt vmcnt(12)
	v_lshlrev_b32_e32 v170, 16, v126
	v_pk_fma_f32 v[176:177], v[138:139], v[170:171], v[176:177]
	global_load_dwordx4 v[34:37], v[38:39], off nt
	v_mul_f32_e32 v18, v177, v177
	v_fmamk_f32 v18, v18, 0xbdd2d3e7, v251
	v_mul_f32_e32 v18, v177, v18
	v_exp_f32_e32 v18, v18
	v_add_co_u32_e32 v38, vcc, s6, v38
	v_lshl_add_u64 v[130:131], s[8:9], 0, v[144:145]
	v_add_f32_e32 v18, 1.0, v18
	v_rcp_f32_e32 v18, v18
	v_addc_co_u32_e32 v39, vcc, 0, v39, vcc
	s_movk_i32 s12, 0x2c00
	v_mul_f32_e32 v18, v177, v18
	v_mul_f32_e32 v187, v176, v18
	v_mov_b32_e32 v18, v115
	v_pk_fma_f32 v[114:115], v[18:19], v[174:175], v[30:31]
	v_and_b32_e32 v177, 0xffff0000, v122
	v_and_b32_e32 v176, 0xffff0000, v126
	v_pk_fma_f32 v[106:107], v[22:23], v[160:161], v[114:115]
	v_mov_b32_e32 v114, v108
	v_pk_fma_f32 v[106:107], v[26:27], v[176:177], v[106:107]
	v_mov_b32_e32 v115, v24
	v_mul_f32_e32 v110, v107, v107
	v_fmamk_f32 v110, v110, 0xbdd2d3e7, v251
	v_mul_f32_e32 v110, v107, v110
	v_exp_f32_e32 v110, v110
	v_lshlrev_b32_e32 v174, 16, v127
	v_lshlrev_b32_e32 v175, 16, v123
	v_mov_b32_e32 v24, v109
	v_add_f32_e32 v110, 1.0, v110
	v_rcp_f32_e32 v110, v110
	v_mov_b32_e32 v126, v96
	global_load_dwordx4 v[38:41], v[38:39], off offset:3072 nt
	s_waitcnt vmcnt(12)
	v_lshlrev_b32_e32 v96, 16, v103
	v_mul_f32_e32 v107, v107, v110
	v_mul_f32_e32 v188, v106, v107
	v_mov_b32_e32 v106, v116
	v_mov_b32_e32 v107, v20
	v_mov_b32_e32 v110, v120
	v_pk_fma_f32 v[118:119], v[106:107], v[172:173], v[110:111]
	v_add_u32_e32 v0, s30, v0
	v_pk_fma_f32 v[172:173], v[114:115], v[158:159], v[118:119]
	v_mov_b32_e32 v118, v112
	v_mov_b32_e32 v119, v28
	v_pk_fma_f32 v[172:173], v[118:119], v[174:175], v[172:173]
	v_mov_b32_e32 v28, v113
	v_mul_f32_e32 v20, v173, v173
	v_fmamk_f32 v20, v20, 0xbdd2d3e7, v251
	v_mul_f32_e32 v20, v173, v20
	v_exp_f32_e32 v20, v20
	v_mov_b32_e32 v113, v14
	v_mov_b32_e32 v14, v95
	v_add_u32_e32 v178, s14, v178
	v_add_f32_e32 v20, 1.0, v20
	v_rcp_f32_e32 v20, v20
	s_nop 0
	v_mul_f32_e32 v20, v173, v20
	v_mul_f32_e32 v189, v172, v20
	v_mov_b32_e32 v20, v117
	v_pk_fma_f32 v[116:117], v[20:21], v[168:169], v[32:33]
	v_and_b32_e32 v173, 0xffff0000, v123
	v_and_b32_e32 v172, 0xffff0000, v127
	v_pk_fma_f32 v[108:109], v[24:25], v[156:157], v[116:117]
	v_mov_b32_e32 v116, v82
	v_pk_fma_f32 v[108:109], v[28:29], v[172:173], v[108:109]
	v_mov_b32_e32 v117, v6
	v_mul_f32_e32 v112, v109, v109
	v_fmamk_f32 v112, v112, 0xbdd2d3e7, v251
	v_mul_f32_e32 v112, v109, v112
	v_exp_f32_e32 v112, v112
	v_lshlrev_b32_e32 v168, 16, v128
	v_lshlrev_b32_e32 v169, 16, v124
	v_mov_b32_e32 v6, v83
	v_add_f32_e32 v112, 1.0, v112
	v_rcp_f32_e32 v112, v112
	v_mov_b32_e32 v127, v16
	v_mov_b32_e32 v16, v97
	v_lshlrev_b32_e32 v97, 16, v99
	v_mul_f32_e32 v109, v109, v112
	v_mul_f32_e32 v190, v108, v109
	v_mov_b32_e32 v108, v90
	v_mov_b32_e32 v109, v2
	v_mov_b32_e32 v112, v94
	v_pk_fma_f32 v[120:121], v[108:109], v[166:167], v[112:113]
	v_and_b32_e32 v167, 0xffff0000, v124
	v_pk_fma_f32 v[122:123], v[116:117], v[154:155], v[120:121]
	v_mov_b32_e32 v120, v86
	v_mov_b32_e32 v121, v10
	v_pk_fma_f32 v[122:123], v[120:121], v[168:169], v[122:123]
	v_and_b32_e32 v166, 0xffff0000, v128
	v_mul_f32_e32 v2, v123, v123
	v_fmamk_f32 v2, v2, 0xbdd2d3e7, v251
	v_mul_f32_e32 v2, v123, v2
	v_exp_f32_e32 v2, v2
	v_mov_b32_e32 v10, v87
	s_waitcnt vmcnt(10)
; __device__ __forceinline__ unsigned cvt_pk_bf16(float lo, float hi) { unsigned r; asm volatile("v_cvt_pk_bf16_f32 %0, %1, %2" : "=v"(r) : "v"(lo), "v"(hi)); return r; }
; __device__ __forceinline__ float gelu_tanh(float x) {
;     const float y = 0.7978845608028654f * (x + 0.044715f * x * x * x);
;     return x * __builtin_amdgcn_rcpf(1.0f + __builtin_amdgcn_exp2f(-2.0f * LOG2E * y));
; }
; __device__ __forceinline__ void phase_conv(const Params& p, int layer) {
;     ...
;         for (int rb = 0; rb < RCH; rb += 8) {
;             u32x4 gr[8], ur[8];
; #pragma unroll
;             for (int k = 0; k < 8; ++k) { gr[k] = __builtin_nontemporal_load((const u32x4*)(U + (size_t)(r0 + rb + k) * DFF2 + c)); ur[k] = __builtin_nontemporal_load((const u32x4*)(U + (size_t)(r0 + rb + k) * DFF2 + DFF + c)); }
; #pragma unroll
;             for (int k = 0; k < 8; ++k) {
;                 float g0[8], u0[8]; unpack8(gr[k], g0); unpack8(ur[k], u0);
;                 float o[8];
; #pragma unroll
;                 for (int e = 0; e < 8; ++e) {
;                     const float gp = bg[e] + wg[0][e] * g2[e] + wg[1][e] * g1[e] + wg[2][e] * g0[e];
;                     const float up = bu[e] + wu[0][e] * u2[e] + wu[1][e] * u1[e] + wu[2][e] * u0[e];
;                     o[e] = gelu_tanh(gp) * up;
;                     g2[e] = g1[e]; g1[e] = g0[e]; u2[e] = u1[e]; u1[e] = u0[e];
;                 }
;                 u32x4 w; w.x = cvt_pk_bf16(o[0], o[1]); w.y = cvt_pk_bf16(o[2], o[3]); w.z = cvt_pk_bf16(o[4], o[5]); w.w = cvt_pk_bf16(o[6], o[7]);
;                 *(u32x4*)(Gd + (size_t)(r0 + rb + k) * DFF + c) = w;
	v_lshlrev_b32_e32 v128, 16, v78
	v_add_f32_e32 v2, 1.0, v2
	v_rcp_f32_e32 v2, v2
	s_nop 0
	v_mul_f32_e32 v2, v123, v2
	v_mul_f32_e32 v94, v122, v2
	v_mov_b32_e32 v2, v91
	v_pk_fma_f32 v[90:91], v[2:3], v[142:143], v[14:15]
	v_mov_b32_e32 v122, v92
	v_pk_fma_f32 v[82:83], v[6:7], v[152:153], v[90:91]
	v_mov_b32_e32 v123, v4
	v_pk_fma_f32 v[82:83], v[10:11], v[166:167], v[82:83]
	v_mov_b32_e32 v142, v88
	v_mul_f32_e32 v86, v83, v83
	v_fmamk_f32 v86, v86, 0xbdd2d3e7, v251
	v_mul_f32_e32 v86, v83, v86
	v_exp_f32_e32 v86, v86
	v_mov_b32_e32 v143, v12
	v_mov_b32_e32 v12, v89
	v_add_f32_e32 v86, 1.0, v86
	v_rcp_f32_e32 v86, v86
	s_nop 0
	v_mul_f32_e32 v83, v83, v86
	v_pk_fma_f32 v[86:87], v[122:123], v[140:141], v[126:127]
	v_mov_b32_e32 v140, v84
	v_mov_b32_e32 v141, v8
	v_mul_f32_e32 v95, v82, v83
	v_lshlrev_b32_e32 v82, 16, v129
	v_lshlrev_b32_e32 v83, 16, v125
	v_pk_fma_f32 v[86:87], v[140:141], v[150:151], v[86:87]
	v_mov_b32_e32 v8, v85
	v_pk_fma_f32 v[86:87], v[142:143], v[82:83], v[86:87]
	s_nop 0
	v_mul_f32_e32 v4, v87, v87
	v_fmamk_f32 v4, v4, 0xbdd2d3e7, v251
	v_mul_f32_e32 v4, v87, v4
	v_exp_f32_e32 v4, v4
	s_nop 0
	v_add_f32_e32 v4, 1.0, v4
	v_rcp_f32_e32 v4, v4
	s_nop 0
	v_mul_f32_e32 v4, v87, v4
	v_mul_f32_e32 v92, v86, v4
	v_mov_b32_e32 v4, v93
	v_pk_fma_f32 v[90:91], v[4:5], v[162:163], v[16:17]
	v_and_b32_e32 v87, 0xffff0000, v125
	v_and_b32_e32 v86, 0xffff0000, v129
	v_pk_fma_f32 v[84:85], v[8:9], v[148:149], v[90:91]
	v_lshlrev_b32_e32 v162, 16, v102
	v_pk_fma_f32 v[84:85], v[12:13], v[86:87], v[84:85]
	v_lshlrev_b32_e32 v163, 16, v98
	v_mul_f32_e32 v88, v85, v85
	v_fmamk_f32 v88, v88, 0xbdd2d3e7, v251
	v_mul_f32_e32 v88, v85, v88
	v_exp_f32_e32 v88, v88
	v_lshlrev_b32_e32 v129, 16, v74
	v_lshlrev_b32_e32 v125, 16, v75
	v_and_b32_e32 v75, 0xffff0000, v75
	v_add_f32_e32 v88, 1.0, v88
	v_rcp_f32_e32 v88, v88
	s_nop 0
	v_mul_f32_e32 v85, v85, v88
	v_mul_f32_e32 v84, v84, v85
	v_cvt_pk_bf16_f32 v88, v187, v188
	v_cvt_pk_bf16_f32 v89, v189, v190
	v_cvt_pk_bf16_f32 v90, v94, v95
	v_cvt_pk_bf16_f32 v91, v92, v84
	v_mad_i64_i32 v[84:85], s[2:3], v179, s12, v[130:131]
	global_store_dwordx4 v[84:85], v[88:91], off
	v_pk_fma_f32 v[84:85], v[132:133], v[164:165], v[134:135]
	s_waitcnt vmcnt(4)
	v_and_b32_e32 v165, 0xffff0000, v42
	v_pk_fma_f32 v[84:85], v[136:137], v[170:171], v[84:85]
	s_waitcnt vmcnt(3)
	v_and_b32_e32 v164, 0xffff0000, v46
	v_pk_fma_f32 v[84:85], v[138:139], v[162:163], v[84:85]
	s_nop 0
	v_mul_f32_e32 v88, v85, v85
	v_fmamk_f32 v88, v88, 0xbdd2d3e7, v251
	v_mul_f32_e32 v88, v85, v88
	v_exp_f32_e32 v88, v88
	s_nop 0
	v_add_f32_e32 v88, 1.0, v88
	v_rcp_f32_e32 v88, v88
	s_nop 0
	v_mul_f32_e32 v85, v85, v88
	v_pk_fma_f32 v[88:89], v[18:19], v[160:161], v[30:31]
	v_mul_f32_e32 v124, v84, v85
	v_and_b32_e32 v85, 0xffff0000, v98
	v_and_b32_e32 v84, 0xffff0000, v102
	v_pk_fma_f32 v[88:89], v[22:23], v[176:177], v[88:89]
	v_lshlrev_b32_e32 v160, 16, v48
	v_pk_fma_f32 v[88:89], v[26:27], v[84:85], v[88:89]
	v_lshlrev_b32_e32 v161, 16, v44
	v_mul_f32_e32 v90, v89, v89
	v_fmamk_f32 v90, v90, 0xbdd2d3e7, v251
	v_mul_f32_e32 v90, v89, v90
	v_exp_f32_e32 v90, v90
	s_nop 0
	v_add_f32_e32 v90, 1.0, v90
	v_rcp_f32_e32 v90, v90
	s_nop 0
	v_mul_f32_e32 v89, v89, v90
	v_mul_f32_e32 v98, v88, v89
	v_pk_fma_f32 v[88:89], v[106:107], v[158:159], v[110:111]
	v_cvt_pk_bf16_f32 v98, v124, v98
	v_lshlrev_b32_e32 v124, 16, v79
	v_pk_fma_f32 v[88:89], v[114:115], v[174:175], v[88:89]
	v_lshlrev_b32_e32 v158, 16, v49
	v_pk_fma_f32 v[88:89], v[118:119], v[96:97], v[88:89]
	v_lshlrev_b32_e32 v159, 16, v45
	v_mul_f32_e32 v90, v89, v89
	v_fmamk_f32 v90, v90, 0xbdd2d3e7, v251
	v_mul_f32_e32 v90, v89, v90
	v_exp_f32_e32 v90, v90
	s_nop 0
	v_add_f32_e32 v90, 1.0, v90
	v_rcp_f32_e32 v90, v90
	s_nop 0
	v_mul_f32_e32 v89, v89, v90
	v_pk_fma_f32 v[90:91], v[20:21], v[156:157], v[32:33]
	v_mul_f32_e32 v102, v88, v89
	v_and_b32_e32 v89, 0xffff0000, v99
	v_and_b32_e32 v88, 0xffff0000, v103
	v_pk_fma_f32 v[90:91], v[24:25], v[172:173], v[90:91]
	v_lshlrev_b32_e32 v156, 16, v104
	v_pk_fma_f32 v[90:91], v[28:29], v[88:89], v[90:91]
	v_lshlrev_b32_e32 v157, 16, v100
	v_mul_f32_e32 v92, v91, v91
	v_fmamk_f32 v92, v92, 0xbdd2d3e7, v251
	v_mul_f32_e32 v92, v91, v92
	v_exp_f32_e32 v92, v92
	s_nop 0
	v_add_f32_e32 v92, 1.0, v92
	v_rcp_f32_e32 v92, v92
	s_nop 0
	v_mul_f32_e32 v91, v91, v92
	v_mul_f32_e32 v99, v90, v91
	v_pk_fma_f32 v[90:91], v[108:109], v[154:155], v[112:113]
	v_cvt_pk_bf16_f32 v99, v102, v99
	v_lshlrev_b32_e32 v102, 16, v81
	v_pk_fma_f32 v[90:91], v[116:117], v[168:169], v[90:91]
	s_waitcnt vmcnt(1)
; __device__ __forceinline__ unsigned cvt_pk_bf16(float lo, float hi) { unsigned r; asm volatile("v_cvt_pk_bf16_f32 %0, %1, %2" : "=v"(r) : "v"(lo), "v"(hi)); return r; }
; __device__ __forceinline__ float gelu_tanh(float x) {
;     const float y = 0.7978845608028654f * (x + 0.044715f * x * x * x);
;     return x * __builtin_amdgcn_rcpf(1.0f + __builtin_amdgcn_exp2f(-2.0f * LOG2E * y));
; }
; __device__ __forceinline__ void phase_conv(const Params& p, int layer) {
;     ...
;         for (int rb = 0; rb < RCH; rb += 8) {
;             u32x4 gr[8], ur[8];
; #pragma unroll
;             for (int k = 0; k < 8; ++k) { gr[k] = __builtin_nontemporal_load((const u32x4*)(U + (size_t)(r0 + rb + k) * DFF2 + c)); ur[k] = __builtin_nontemporal_load((const u32x4*)(U + (size_t)(r0 + rb + k) * DFF2 + DFF + c)); }
; #pragma unroll
;             for (int k = 0; k < 8; ++k) {
;                 float g0[8], u0[8]; unpack8(gr[k], g0); unpack8(ur[k], u0);
;                 float o[8];
; #pragma unroll
;                 for (int e = 0; e < 8; ++e) {
;                     const float gp = bg[e] + wg[0][e] * g2[e] + wg[1][e] * g1[e] + wg[2][e] * g0[e];
;                     const float up = bu[e] + wu[0][e] * u2[e] + wu[1][e] * u1[e] + wu[2][e] * u0[e];
;                     o[e] = gelu_tanh(gp) * up;
;                     g2[e] = g1[e]; g1[e] = g0[e]; u2[e] = u1[e]; u1[e] = u0[e];
;                 }
;                 u32x4 w; w.x = cvt_pk_bf16(o[0], o[1]); w.y = cvt_pk_bf16(o[2], o[3]); w.z = cvt_pk_bf16(o[4], o[5]); w.w = cvt_pk_bf16(o[6], o[7]);
;                 *(u32x4*)(Gd + (size_t)(r0 + rb + k) * DFF + c) = w;
	v_lshlrev_b32_e32 v154, 16, v39
	v_pk_fma_f32 v[90:91], v[120:121], v[156:157], v[90:91]
	v_lshlrev_b32_e32 v155, 16, v35
	v_mul_f32_e32 v92, v91, v91
	v_fmamk_f32 v92, v92, 0xbdd2d3e7, v251
	v_mul_f32_e32 v92, v91, v92
	v_exp_f32_e32 v92, v92
	s_nop 0
	v_add_f32_e32 v92, 1.0, v92
	v_rcp_f32_e32 v92, v92
	s_nop 0
	v_mul_f32_e32 v91, v91, v92
	v_pk_fma_f32 v[92:93], v[2:3], v[152:153], v[14:15]
	v_mul_f32_e32 v103, v90, v91
	v_and_b32_e32 v91, 0xffff0000, v100
	v_and_b32_e32 v90, 0xffff0000, v104
	v_pk_fma_f32 v[92:93], v[6:7], v[166:167], v[92:93]
	v_lshlrev_b32_e32 v152, 16, v105
	v_pk_fma_f32 v[92:93], v[10:11], v[90:91], v[92:93]
	v_lshlrev_b32_e32 v153, 16, v101
	v_mul_f32_e32 v94, v93, v93
	v_fmamk_f32 v94, v94, 0xbdd2d3e7, v251
	v_mul_f32_e32 v94, v93, v94
	v_exp_f32_e32 v94, v94
	s_nop 0
	v_add_f32_e32 v94, 1.0, v94
	v_rcp_f32_e32 v94, v94
	s_nop 0
	v_mul_f32_e32 v93, v93, v94
	v_mul_f32_e32 v100, v92, v93
	v_pk_fma_f32 v[92:93], v[122:123], v[150:151], v[126:127]
	v_cvt_pk_bf16_f32 v100, v103, v100
	v_lshlrev_b32_e32 v103, 16, v77
	v_pk_fma_f32 v[92:93], v[140:141], v[82:83], v[92:93]
	v_pk_fma_f32 v[82:83], v[122:123], v[82:83], v[126:127]
	v_pk_fma_f32 v[92:93], v[142:143], v[152:153], v[92:93]
	v_pk_fma_f32 v[82:83], v[140:141], v[152:153], v[82:83]
	v_mul_f32_e32 v94, v93, v93
	v_fmamk_f32 v94, v94, 0xbdd2d3e7, v251
	v_mul_f32_e32 v94, v93, v94
	v_exp_f32_e32 v94, v94
	v_pk_fma_f32 v[82:83], v[142:143], v[102:103], v[82:83]
	v_and_b32_e32 v77, 0xffff0000, v77
	v_lshlrev_b32_e32 v151, 16, v37
	v_add_f32_e32 v94, 1.0, v94
	v_rcp_f32_e32 v94, v94
	s_nop 0
	v_mul_f32_e32 v93, v93, v94
	v_pk_fma_f32 v[94:95], v[4:5], v[148:149], v[16:17]
	v_mul_f32_e32 v104, v92, v93
	v_and_b32_e32 v93, 0xffff0000, v101
	v_and_b32_e32 v92, 0xffff0000, v105
	v_pk_fma_f32 v[94:95], v[8:9], v[86:87], v[94:95]
	v_lshlrev_b32_e32 v105, 16, v76
	v_pk_fma_f32 v[94:95], v[12:13], v[92:93], v[94:95]
	s_nop 0
	v_mul_f32_e32 v101, v95, v95
	v_fmamk_f32 v101, v101, 0xbdd2d3e7, v251
	v_mul_f32_e32 v101, v95, v101
	v_exp_f32_e32 v101, v101
	s_nop 0
	v_add_f32_e32 v101, 1.0, v101
	v_rcp_f32_e32 v101, v101
	s_nop 0
	v_mul_f32_e32 v95, v95, v101
	v_mul_f32_e32 v94, v94, v95
	v_cvt_pk_bf16_f32 v101, v104, v94
	v_mad_i64_i32 v[94:95], s[2:3], v186, s12, v[130:131]
	global_store_dwordx4 v[94:95], v[98:101], off
	v_pk_fma_f32 v[94:95], v[132:133], v[170:171], v[134:135]
	v_lshlrev_b32_e32 v104, 16, v80
	v_pk_fma_f32 v[94:95], v[136:137], v[162:163], v[94:95]
	v_or_b32_e32 v171, 12, v179
	v_pk_fma_f32 v[94:95], v[138:139], v[128:129], v[94:95]
	v_or_b32_e32 v170, 13, v179
	v_mul_f32_e32 v98, v95, v95
	v_fmamk_f32 v98, v98, 0xbdd2d3e7, v251
	v_mul_f32_e32 v98, v95, v98
	v_exp_f32_e32 v98, v98
	s_nop 0
	v_add_f32_e32 v98, 1.0, v98
	v_rcp_f32_e32 v98, v98
	s_nop 0
	v_mul_f32_e32 v95, v95, v98
	v_pk_fma_f32 v[98:99], v[18:19], v[176:177], v[30:31]
	v_mul_f32_e32 v100, v94, v95
	v_and_b32_e32 v95, 0xffff0000, v74
	v_and_b32_e32 v94, 0xffff0000, v78
	v_pk_fma_f32 v[98:99], v[22:23], v[84:85], v[98:99]
	s_nop 0
	v_pk_fma_f32 v[98:99], v[26:27], v[94:95], v[98:99]
	s_nop 0
	v_mul_f32_e32 v74, v99, v99
	v_fmamk_f32 v74, v74, 0xbdd2d3e7, v251
	v_mul_f32_e32 v74, v99, v74
	v_exp_f32_e32 v74, v74
	s_nop 0
	v_add_f32_e32 v74, 1.0, v74
	v_rcp_f32_e32 v74, v74
	s_nop 0
	v_mul_f32_e32 v74, v99, v74
	v_mul_f32_e32 v101, v98, v74
	v_pk_fma_f32 v[98:99], v[106:107], v[174:175], v[110:111]
	v_or_b32_e32 v175, 8, v179
	v_pk_fma_f32 v[98:99], v[114:115], v[96:97], v[98:99]
	v_or_b32_e32 v174, 9, v179
	v_pk_fma_f32 v[98:99], v[118:119], v[124:125], v[98:99]
	s_nop 0
	v_mul_f32_e32 v74, v99, v99
	v_fmamk_f32 v74, v74, 0xbdd2d3e7, v251
	v_mul_f32_e32 v74, v99, v74
	v_exp_f32_e32 v74, v74
	s_nop 0
	v_add_f32_e32 v74, 1.0, v74
	v_rcp_f32_e32 v74, v74
	s_nop 0
	v_mul_f32_e32 v74, v99, v74
	v_mul_f32_e32 v148, v98, v74
	v_and_b32_e32 v74, 0xffff0000, v79
	v_pk_fma_f32 v[78:79], v[20:21], v[172:173], v[32:33]
	v_or_b32_e32 v173, 10, v179
	v_pk_fma_f32 v[78:79], v[24:25], v[88:89], v[78:79]
	v_or_b32_e32 v172, 11, v179
	v_pk_fma_f32 v[78:79], v[28:29], v[74:75], v[78:79]
	s_nop 0
	v_mul_f32_e32 v98, v79, v79
	v_fmamk_f32 v98, v98, 0xbdd2d3e7, v251
	v_mul_f32_e32 v98, v79, v98
	v_exp_f32_e32 v98, v98
	s_nop 0
	v_add_f32_e32 v98, 1.0, v98
	v_rcp_f32_e32 v98, v98
	s_nop 0
	v_mul_f32_e32 v79, v79, v98
	v_mul_f32_e32 v149, v78, v79
	v_pk_fma_f32 v[78:79], v[108:109], v[168:169], v[112:113]
	v_or_b32_e32 v169, 14, v179
	v_pk_fma_f32 v[78:79], v[116:117], v[156:157], v[78:79]
	v_or_b32_e32 v168, 15, v179
	v_pk_fma_f32 v[78:79], v[120:121], v[104:105], v[78:79]
	s_nop 0
	v_mul_f32_e32 v98, v79, v79
	v_fmamk_f32 v98, v98, 0xbdd2d3e7, v251
	v_mul_f32_e32 v98, v79, v98
	v_exp_f32_e32 v98, v98
	s_nop 0
	v_add_f32_e32 v98, 1.0, v98
	v_rcp_f32_e32 v98, v98
	s_nop 0
	v_mul_f32_e32 v79, v79, v98
	v_pk_fma_f32 v[98:99], v[2:3], v[166:167], v[14:15]
	v_mul_f32_e32 v150, v78, v79
	v_and_b32_e32 v79, 0xffff0000, v76
	v_and_b32_e32 v78, 0xffff0000, v80
	v_pk_fma_f32 v[98:99], v[6:7], v[90:91], v[98:99]
	v_lshlrev_b32_e32 v166, 16, v46
	v_pk_fma_f32 v[98:99], v[10:11], v[78:79], v[98:99]
	v_lshlrev_b32_e32 v167, 16, v42
	v_mul_f32_e32 v76, v99, v99
	v_fmamk_f32 v76, v76, 0xbdd2d3e7, v251
	v_mul_f32_e32 v76, v99, v76
	v_exp_f32_e32 v76, v76
	s_nop 0
	v_add_f32_e32 v76, 1.0, v76
	v_rcp_f32_e32 v76, v76
	s_nop 0
	v_mul_f32_e32 v76, v99, v76
	v_mul_f32_e32 v98, v98, v76
	v_mul_f32_e32 v76, v83, v83
	v_fmamk_f32 v76, v76, 0xbdd2d3e7, v251
	v_mul_f32_e32 v76, v83, v76
	v_exp_f32_e32 v76, v76
	v_lshlrev_b32_e32 v99, 16, v67
	v_and_b32_e32 v67, 0xffff0000, v67
	v_add_f32_e32 v76, 1.0, v76
	v_rcp_f32_e32 v76, v76
	s_nop 0
; __device__ __forceinline__ unsigned cvt_pk_bf16(float lo, float hi) { unsigned r; asm volatile("v_cvt_pk_bf16_f32 %0, %1, %2" : "=v"(r) : "v"(lo), "v"(hi)); return r; }
; __device__ __forceinline__ float gelu_tanh(float x) {
;     const float y = 0.7978845608028654f * (x + 0.044715f * x * x * x);
;     return x * __builtin_amdgcn_rcpf(1.0f + __builtin_amdgcn_exp2f(-2.0f * LOG2E * y));
; }
; __device__ __forceinline__ void phase_conv(const Params& p, int layer) {
;     ...
;         for (int rb = 0; rb < RCH; rb += 8) {
;             u32x4 gr[8], ur[8];
; #pragma unroll
;             for (int k = 0; k < 8; ++k) { gr[k] = __builtin_nontemporal_load((const u32x4*)(U + (size_t)(r0 + rb + k) * DFF2 + c)); ur[k] = __builtin_nontemporal_load((const u32x4*)(U + (size_t)(r0 + rb + k) * DFF2 + DFF + c)); }
; #pragma unroll
;             for (int k = 0; k < 8; ++k) {
;                 float g0[8], u0[8]; unpack8(gr[k], g0); unpack8(ur[k], u0);
;                 float o[8];
; #pragma unroll
;                 for (int e = 0; e < 8; ++e) {
;                     const float gp = bg[e] + wg[0][e] * g2[e] + wg[1][e] * g1[e] + wg[2][e] * g0[e];
;                     const float up = bu[e] + wu[0][e] * u2[e] + wu[1][e] * u1[e] + wu[2][e] * u0[e];
;                     o[e] = gelu_tanh(gp) * up;
;                     g2[e] = g1[e]; g1[e] = g0[e]; u2[e] = u1[e]; u1[e] = u0[e];
;                 }
;                 u32x4 w; w.x = cvt_pk_bf16(o[0], o[1]); w.y = cvt_pk_bf16(o[2], o[3]); w.z = cvt_pk_bf16(o[4], o[5]); w.w = cvt_pk_bf16(o[6], o[7]);
;                 *(u32x4*)(Gd + (size_t)(r0 + rb + k) * DFF + c) = w;
;             }
;         }
	v_mul_f32_e32 v76, v83, v76
	v_mul_f32_e32 v83, v82, v76
	v_and_b32_e32 v76, 0xffff0000, v81
	v_pk_fma_f32 v[80:81], v[4:5], v[86:87], v[16:17]
	s_nop 0
	v_pk_fma_f32 v[80:81], v[8:9], v[92:93], v[80:81]
	s_nop 0
	v_pk_fma_f32 v[80:81], v[12:13], v[76:77], v[80:81]
	s_nop 0
	v_mul_f32_e32 v82, v81, v81
	v_fmamk_f32 v82, v82, 0xbdd2d3e7, v251
	v_mul_f32_e32 v82, v81, v82
	v_exp_f32_e32 v82, v82
	s_nop 0
	v_add_f32_e32 v82, 1.0, v82
	v_rcp_f32_e32 v82, v82
	s_nop 0
	v_mul_f32_e32 v81, v81, v82
	v_mul_f32_e32 v86, v80, v81
	v_cvt_pk_bf16_f32 v80, v100, v101
	v_cvt_pk_bf16_f32 v81, v148, v149
	v_cvt_pk_bf16_f32 v82, v150, v98
	v_cvt_pk_bf16_f32 v83, v83, v86
	v_mad_i64_i32 v[86:87], s[2:3], v185, s12, v[130:131]
	global_store_dwordx4 v[86:87], v[80:83], off
	v_lshlrev_b32_e32 v100, 16, v70
	v_lshlrev_b32_e32 v101, 16, v66
	v_pk_fma_f32 v[80:81], v[132:133], v[162:163], v[134:135]
	v_lshlrev_b32_e32 v98, 16, v71
	v_pk_fma_f32 v[80:81], v[136:137], v[128:129], v[80:81]
	v_lshlrev_b32_e32 v162, 16, v47
	v_pk_fma_f32 v[80:81], v[138:139], v[100:101], v[80:81]
	v_lshlrev_b32_e32 v163, 16, v43
	v_mul_f32_e32 v82, v81, v81
	v_fmamk_f32 v82, v82, 0xbdd2d3e7, v251
	v_mul_f32_e32 v82, v81, v82
	v_exp_f32_e32 v82, v82
	v_lshlrev_b32_e32 v150, 16, v41
	v_and_b32_e32 v149, 0xffff0000, v37
	v_add_f32_e32 v82, 1.0, v82
	v_rcp_f32_e32 v82, v82
	s_nop 0
	v_mul_f32_e32 v81, v81, v82
	v_pk_fma_f32 v[82:83], v[18:19], v[84:85], v[30:31]
	v_mul_f32_e32 v86, v80, v81
	v_and_b32_e32 v81, 0xffff0000, v66
	v_and_b32_e32 v80, 0xffff0000, v70
	v_pk_fma_f32 v[82:83], v[22:23], v[94:95], v[82:83]
	s_nop 0
	v_pk_fma_f32 v[82:83], v[26:27], v[80:81], v[82:83]
	s_nop 0
	v_mul_f32_e32 v66, v83, v83
	v_fmamk_f32 v66, v66, 0xbdd2d3e7, v251
	v_mul_f32_e32 v66, v83, v66
	v_exp_f32_e32 v66, v66
	s_nop 0
	v_add_f32_e32 v66, 1.0, v66
	v_rcp_f32_e32 v66, v66
	s_nop 0
	v_mul_f32_e32 v66, v83, v66
	v_mul_f32_e32 v84, v82, v66
	v_pk_fma_f32 v[82:83], v[106:107], v[96:97], v[110:111]
	v_lshlrev_b32_e32 v96, 16, v72
	v_pk_fma_f32 v[82:83], v[114:115], v[124:125], v[82:83]
	v_lshlrev_b32_e32 v97, 16, v68
	v_pk_fma_f32 v[82:83], v[118:119], v[98:99], v[82:83]
	s_nop 0
	v_mul_f32_e32 v66, v83, v83
	v_fmamk_f32 v66, v66, 0xbdd2d3e7, v251
	v_mul_f32_e32 v66, v83, v66
	v_exp_f32_e32 v66, v66
	s_nop 0
	v_add_f32_e32 v66, 1.0, v66
	v_rcp_f32_e32 v66, v66
	s_nop 0
	v_mul_f32_e32 v66, v83, v66
	v_mul_f32_e32 v85, v82, v66
	v_and_b32_e32 v66, 0xffff0000, v71
	v_pk_fma_f32 v[70:71], v[20:21], v[88:89], v[32:33]
	s_nop 0
	v_pk_fma_f32 v[70:71], v[24:25], v[74:75], v[70:71]
	s_nop 0
	v_pk_fma_f32 v[70:71], v[28:29], v[66:67], v[70:71]
	s_nop 0
	v_mul_f32_e32 v82, v71, v71
	v_fmamk_f32 v82, v82, 0xbdd2d3e7, v251
	v_mul_f32_e32 v82, v71, v82
	v_exp_f32_e32 v82, v82
	s_nop 0
	v_add_f32_e32 v82, 1.0, v82
	v_rcp_f32_e32 v82, v82
	s_nop 0
	v_mul_f32_e32 v71, v71, v82
	v_mul_f32_e32 v87, v70, v71
	v_pk_fma_f32 v[70:71], v[108:109], v[156:157], v[112:113]
	v_lshlrev_b32_e32 v156, 16, v38
	v_pk_fma_f32 v[70:71], v[116:117], v[104:105], v[70:71]
	v_lshlrev_b32_e32 v157, 16, v34
	v_pk_fma_f32 v[70:71], v[120:121], v[96:97], v[70:71]
	s_nop 0
	v_mul_f32_e32 v82, v71, v71
	v_fmamk_f32 v82, v82, 0xbdd2d3e7, v251
	v_mul_f32_e32 v82, v71, v82
	v_exp_f32_e32 v82, v82
	s_nop 0
	v_add_f32_e32 v82, 1.0, v82
	v_rcp_f32_e32 v82, v82
	s_nop 0
	v_mul_f32_e32 v71, v71, v82
	v_pk_fma_f32 v[82:83], v[2:3], v[90:91], v[14:15]
	v_mul_f32_e32 v88, v70, v71
	v_and_b32_e32 v71, 0xffff0000, v68
	v_and_b32_e32 v70, 0xffff0000, v72
	v_pk_fma_f32 v[82:83], v[6:7], v[78:79], v[82:83]
	v_lshlrev_b32_e32 v90, 16, v73
	v_pk_fma_f32 v[82:83], v[10:11], v[70:71], v[82:83]
	v_lshlrev_b32_e32 v91, 16, v69
	v_mul_f32_e32 v68, v83, v83
	v_fmamk_f32 v68, v68, 0xbdd2d3e7, v251
	v_mul_f32_e32 v68, v83, v68
	v_exp_f32_e32 v68, v68
	v_and_b32_e32 v69, 0xffff0000, v69
	v_add_f32_e32 v68, 1.0, v68
	v_rcp_f32_e32 v68, v68
	s_nop 0
	v_mul_f32_e32 v68, v83, v68
	v_mul_f32_e32 v89, v82, v68
	v_pk_fma_f32 v[82:83], v[122:123], v[152:153], v[126:127]
	v_lshlrev_b32_e32 v152, 16, v40
	v_pk_fma_f32 v[82:83], v[140:141], v[102:103], v[82:83]
	v_lshlrev_b32_e32 v153, 16, v36
	v_pk_fma_f32 v[82:83], v[142:143], v[90:91], v[82:83]
	s_nop 0
	v_mul_f32_e32 v68, v83, v83
	v_fmamk_f32 v68, v68, 0xbdd2d3e7, v251
	v_mul_f32_e32 v68, v83, v68
	v_exp_f32_e32 v68, v68
	s_nop 0
	v_add_f32_e32 v68, 1.0, v68
	v_rcp_f32_e32 v68, v68
	s_nop 0
	v_mul_f32_e32 v68, v83, v68
	v_mul_f32_e32 v148, v82, v68
	v_and_b32_e32 v68, 0xffff0000, v73
	v_pk_fma_f32 v[72:73], v[4:5], v[92:93], v[16:17]
	s_nop 0
	v_pk_fma_f32 v[72:73], v[8:9], v[76:77], v[72:73]
	s_nop 0
	v_pk_fma_f32 v[72:73], v[12:13], v[68:69], v[72:73]
	s_nop 0
	v_mul_f32_e32 v82, v73, v73
	v_fmamk_f32 v82, v82, 0xbdd2d3e7, v251
	v_mul_f32_e32 v82, v73, v82
	v_exp_f32_e32 v82, v82
	s_nop 0
	v_add_f32_e32 v82, 1.0, v82
	v_rcp_f32_e32 v82, v82
	s_nop 0
	v_mul_f32_e32 v73, v73, v82
	v_mul_f32_e32 v72, v72, v73
	v_cvt_pk_bf16_f32 v82, v86, v84
	v_cvt_pk_bf16_f32 v83, v85, v87
	v_cvt_pk_bf16_f32 v84, v88, v89
	v_cvt_pk_bf16_f32 v85, v148, v72
	v_mad_i64_i32 v[72:73], s[2:3], v184, s12, v[130:131]
	global_store_dwordx4 v[72:73], v[82:85], off
	v_pk_fma_f32 v[72:73], v[132:133], v[128:129], v[134:135]
	v_lshlrev_b32_e32 v88, 16, v62
	v_lshlrev_b32_e32 v89, 16, v58
	v_pk_fma_f32 v[72:73], v[136:137], v[100:101], v[72:73]
	v_lshlrev_b32_e32 v86, 16, v63
	v_pk_fma_f32 v[72:73], v[138:139], v[88:89], v[72:73]
	v_lshlrev_b32_e32 v87, 16, v59
	v_mul_f32_e32 v82, v73, v73
	v_fmamk_f32 v82, v82, 0xbdd2d3e7, v251
	v_mul_f32_e32 v82, v73, v82
	v_exp_f32_e32 v82, v82
	v_and_b32_e32 v59, 0xffff0000, v59
	v_lshlrev_b32_e32 v84, 16, v64
; __device__ __forceinline__ unsigned cvt_pk_bf16(float lo, float hi) { unsigned r; asm volatile("v_cvt_pk_bf16_f32 %0, %1, %2" : "=v"(r) : "v"(lo), "v"(hi)); return r; }
; __device__ __forceinline__ float gelu_tanh(float x) {
;     const float y = 0.7978845608028654f * (x + 0.044715f * x * x * x);
;     return x * __builtin_amdgcn_rcpf(1.0f + __builtin_amdgcn_exp2f(-2.0f * LOG2E * y));
; }
; __device__ __forceinline__ void phase_conv(const Params& p, int layer) {
;     ...
;         for (int rb = 0; rb < RCH; rb += 8) {
;             u32x4 gr[8], ur[8];
; #pragma unroll
;             for (int k = 0; k < 8; ++k) { gr[k] = __builtin_nontemporal_load((const u32x4*)(U + (size_t)(r0 + rb + k) * DFF2 + c)); ur[k] = __builtin_nontemporal_load((const u32x4*)(U + (size_t)(r0 + rb + k) * DFF2 + DFF + c)); }
; #pragma unroll
;             for (int k = 0; k < 8; ++k) {
;                 float g0[8], u0[8]; unpack8(gr[k], g0); unpack8(ur[k], u0);
;                 float o[8];
; #pragma unroll
;                 for (int e = 0; e < 8; ++e) {
;                     const float gp = bg[e] + wg[0][e] * g2[e] + wg[1][e] * g1[e] + wg[2][e] * g0[e];
;                     const float up = bu[e] + wu[0][e] * u2[e] + wu[1][e] * u1[e] + wu[2][e] * u0[e];
;                     o[e] = gelu_tanh(gp) * up;
;                     g2[e] = g1[e]; g1[e] = g0[e]; u2[e] = u1[e]; u1[e] = u0[e];
;                 }
;                 u32x4 w; w.x = cvt_pk_bf16(o[0], o[1]); w.y = cvt_pk_bf16(o[2], o[3]); w.z = cvt_pk_bf16(o[4], o[5]); w.w = cvt_pk_bf16(o[6], o[7]);
;                 *(u32x4*)(Gd + (size_t)(r0 + rb + k) * DFF + c) = w;
;             }
;         }
	v_lshlrev_b32_e32 v85, 16, v60
	v_add_f32_e32 v82, 1.0, v82
	v_rcp_f32_e32 v82, v82
	v_and_b32_e32 v129, 0xffff0000, v36
	v_and_b32_e32 v128, 0xffff0000, v40
	v_and_b32_e32 v148, 0xffff0000, v41
	v_mul_f32_e32 v73, v73, v82
	v_pk_fma_f32 v[82:83], v[18:19], v[94:95], v[30:31]
	v_mul_f32_e32 v92, v72, v73
	v_and_b32_e32 v73, 0xffff0000, v58
	v_and_b32_e32 v72, 0xffff0000, v62
	v_pk_fma_f32 v[82:83], v[22:23], v[80:81], v[82:83]
	s_nop 0
	v_pk_fma_f32 v[82:83], v[26:27], v[72:73], v[82:83]
	s_nop 0
	v_mul_f32_e32 v58, v83, v83
	v_fmamk_f32 v58, v58, 0xbdd2d3e7, v251
	v_mul_f32_e32 v58, v83, v58
	v_exp_f32_e32 v58, v58
	s_nop 0
	v_add_f32_e32 v58, 1.0, v58
	v_rcp_f32_e32 v58, v58
	s_nop 0
	v_mul_f32_e32 v58, v83, v58
	v_mul_f32_e32 v93, v82, v58
	v_pk_fma_f32 v[82:83], v[106:107], v[124:125], v[110:111]
	v_and_b32_e32 v125, 0xffff0000, v35
	v_pk_fma_f32 v[82:83], v[114:115], v[98:99], v[82:83]
	v_and_b32_e32 v124, 0xffff0000, v39
	v_pk_fma_f32 v[82:83], v[118:119], v[86:87], v[82:83]
	s_nop 0
	v_mul_f32_e32 v58, v83, v83
	v_fmamk_f32 v58, v58, 0xbdd2d3e7, v251
	v_mul_f32_e32 v58, v83, v58
	v_exp_f32_e32 v58, v58
	s_nop 0
	v_add_f32_e32 v58, 1.0, v58
	v_rcp_f32_e32 v58, v58
	s_nop 0
	v_mul_f32_e32 v58, v83, v58
	v_mul_f32_e32 v94, v82, v58
	v_and_b32_e32 v58, 0xffff0000, v63
	v_pk_fma_f32 v[62:63], v[20:21], v[74:75], v[32:33]
	v_lshlrev_b32_e32 v82, 16, v65
	v_pk_fma_f32 v[62:63], v[24:25], v[66:67], v[62:63]
	v_lshlrev_b32_e32 v83, 16, v61
	v_pk_fma_f32 v[62:63], v[28:29], v[58:59], v[62:63]
	v_and_b32_e32 v61, 0xffff0000, v61
	v_mul_f32_e32 v74, v63, v63
	v_fmamk_f32 v74, v74, 0xbdd2d3e7, v251
	v_mul_f32_e32 v74, v63, v74
	v_exp_f32_e32 v74, v74
	s_nop 0
	v_add_f32_e32 v74, 1.0, v74
	v_rcp_f32_e32 v74, v74
	s_nop 0
	v_mul_f32_e32 v63, v63, v74
	v_mul_f32_e32 v95, v62, v63
	v_pk_fma_f32 v[62:63], v[108:109], v[104:105], v[112:113]
	v_and_b32_e32 v105, 0xffff0000, v34
	v_pk_fma_f32 v[62:63], v[116:117], v[96:97], v[62:63]
	s_nop 0
	v_pk_fma_f32 v[62:63], v[120:121], v[84:85], v[62:63]
	s_nop 0
	v_mul_f32_e32 v74, v63, v63
	v_fmamk_f32 v74, v74, 0xbdd2d3e7, v251
	v_mul_f32_e32 v74, v63, v74
	v_exp_f32_e32 v74, v74
	s_nop 0
	v_add_f32_e32 v74, 1.0, v74
	v_rcp_f32_e32 v74, v74
	s_nop 0
	v_mul_f32_e32 v63, v63, v74
	v_pk_fma_f32 v[74:75], v[2:3], v[78:79], v[14:15]
	v_mul_f32_e32 v104, v62, v63
	v_and_b32_e32 v63, 0xffff0000, v60
	v_and_b32_e32 v62, 0xffff0000, v64
	v_pk_fma_f32 v[74:75], v[6:7], v[70:71], v[74:75]
	s_nop 0
	v_pk_fma_f32 v[74:75], v[10:11], v[62:63], v[74:75]
	s_nop 0
	v_mul_f32_e32 v60, v75, v75
	v_fmamk_f32 v60, v60, 0xbdd2d3e7, v251
	v_mul_f32_e32 v60, v75, v60
	v_exp_f32_e32 v60, v60
	s_nop 0
	v_add_f32_e32 v60, 1.0, v60
	v_rcp_f32_e32 v60, v60
	s_nop 0
	v_mul_f32_e32 v60, v75, v60
	v_mul_f32_e32 v78, v74, v60
	v_pk_fma_f32 v[74:75], v[122:123], v[102:103], v[126:127]
	v_and_b32_e32 v103, 0xffff0000, v45
	v_pk_fma_f32 v[74:75], v[140:141], v[90:91], v[74:75]
	v_and_b32_e32 v102, 0xffff0000, v49
	v_pk_fma_f32 v[74:75], v[142:143], v[82:83], v[74:75]
	s_nop 0
	v_mul_f32_e32 v60, v75, v75
	v_fmamk_f32 v60, v60, 0xbdd2d3e7, v251
	v_mul_f32_e32 v60, v75, v60
	v_exp_f32_e32 v60, v60
	s_nop 0
	v_add_f32_e32 v60, 1.0, v60
	v_rcp_f32_e32 v60, v60
	s_nop 0
	v_mul_f32_e32 v60, v75, v60
	v_mul_f32_e32 v79, v74, v60
	v_and_b32_e32 v60, 0xffff0000, v65
	v_pk_fma_f32 v[64:65], v[4:5], v[76:77], v[16:17]
	s_nop 0
	v_pk_fma_f32 v[64:65], v[8:9], v[68:69], v[64:65]
	s_nop 0
	v_pk_fma_f32 v[64:65], v[12:13], v[60:61], v[64:65]
	s_nop 0
	v_mul_f32_e32 v74, v65, v65
	v_fmamk_f32 v74, v74, 0xbdd2d3e7, v251
	v_mul_f32_e32 v74, v65, v74
	v_exp_f32_e32 v74, v74
	s_nop 0
	v_add_f32_e32 v74, 1.0, v74
	v_rcp_f32_e32 v74, v74
	s_nop 0
	v_mul_f32_e32 v65, v65, v74
	v_mul_f32_e32 v64, v64, v65
	v_cvt_pk_bf16_f32 v74, v92, v93
	v_cvt_pk_bf16_f32 v75, v94, v95
	v_cvt_pk_bf16_f32 v76, v104, v78
	v_cvt_pk_bf16_f32 v77, v79, v64
	v_mad_i64_i32 v[64:65], s[2:3], v183, s12, v[130:131]
	global_store_dwordx4 v[64:65], v[74:77], off
	v_pk_fma_f32 v[64:65], v[132:133], v[100:101], v[134:135]
	v_lshlrev_b32_e32 v78, 16, v54
	v_lshlrev_b32_e32 v79, 16, v50
	v_pk_fma_f32 v[64:65], v[136:137], v[88:89], v[64:65]
	v_lshlrev_b32_e32 v76, 16, v55
	v_pk_fma_f32 v[64:65], v[138:139], v[78:79], v[64:65]
	v_lshlrev_b32_e32 v77, 16, v51
	v_mul_f32_e32 v74, v65, v65
	v_fmamk_f32 v74, v74, 0xbdd2d3e7, v251
	v_mul_f32_e32 v74, v65, v74
	v_exp_f32_e32 v74, v74
	v_and_b32_e32 v51, 0xffff0000, v51
	v_and_b32_e32 v101, 0xffff0000, v44
	v_and_b32_e32 v100, 0xffff0000, v48
	v_add_f32_e32 v74, 1.0, v74
	v_rcp_f32_e32 v74, v74
	v_and_b32_e32 v104, 0xffff0000, v38
	v_mul_f32_e32 v65, v65, v74
	v_pk_fma_f32 v[74:75], v[18:19], v[80:81], v[30:31]
	v_mul_f32_e32 v92, v64, v65
	v_and_b32_e32 v65, 0xffff0000, v50
	v_and_b32_e32 v64, 0xffff0000, v54
	v_pk_fma_f32 v[74:75], v[22:23], v[72:73], v[74:75]
	s_nop 0
	v_pk_fma_f32 v[74:75], v[26:27], v[64:65], v[74:75]
	s_nop 0
	v_mul_f32_e32 v50, v75, v75
	v_fmamk_f32 v50, v50, 0xbdd2d3e7, v251
	v_mul_f32_e32 v50, v75, v50
	v_exp_f32_e32 v50, v50
	s_nop 0
	v_add_f32_e32 v50, 1.0, v50
	v_rcp_f32_e32 v50, v50
	s_nop 0
	v_mul_f32_e32 v50, v75, v50
	v_mul_f32_e32 v80, v74, v50
	v_pk_fma_f32 v[74:75], v[106:107], v[98:99], v[110:111]
	v_and_b32_e32 v99, 0xffff0000, v43
	v_pk_fma_f32 v[74:75], v[114:115], v[86:87], v[74:75]
	v_and_b32_e32 v98, 0xffff0000, v47
	v_pk_fma_f32 v[74:75], v[118:119], v[76:77], v[74:75]
	s_nop 0
	v_mul_f32_e32 v50, v75, v75
	v_fmamk_f32 v50, v50, 0xbdd2d3e7, v251
	v_mul_f32_e32 v50, v75, v50
	v_exp_f32_e32 v50, v50
	s_nop 0
	v_add_f32_e32 v50, 1.0, v50
	v_rcp_f32_e32 v50, v50
	s_nop 0
	v_mul_f32_e32 v50, v75, v50
; __device__ __forceinline__ unsigned cvt_pk_bf16(float lo, float hi) { unsigned r; asm volatile("v_cvt_pk_bf16_f32 %0, %1, %2" : "=v"(r) : "v"(lo), "v"(hi)); return r; }
; __device__ __forceinline__ float gelu_tanh(float x) {
;     const float y = 0.7978845608028654f * (x + 0.044715f * x * x * x);
;     return x * __builtin_amdgcn_rcpf(1.0f + __builtin_amdgcn_exp2f(-2.0f * LOG2E * y));
; }
; __device__ __forceinline__ void phase_conv(const Params& p, int layer) {
;     ...
;         for (int rb = 0; rb < RCH; rb += 8) {
;             u32x4 gr[8], ur[8];
; #pragma unroll
;             for (int k = 0; k < 8; ++k) { gr[k] = __builtin_nontemporal_load((const u32x4*)(U + (size_t)(r0 + rb + k) * DFF2 + c)); ur[k] = __builtin_nontemporal_load((const u32x4*)(U + (size_t)(r0 + rb + k) * DFF2 + DFF + c)); }
; #pragma unroll
;             for (int k = 0; k < 8; ++k) {
;                 float g0[8], u0[8]; unpack8(gr[k], g0); unpack8(ur[k], u0);
;                 float o[8];
; #pragma unroll
;                 for (int e = 0; e < 8; ++e) {
;                     const float gp = bg[e] + wg[0][e] * g2[e] + wg[1][e] * g1[e] + wg[2][e] * g0[e];
;                     const float up = bu[e] + wu[0][e] * u2[e] + wu[1][e] * u1[e] + wu[2][e] * u0[e];
;                     o[e] = gelu_tanh(gp) * up;
;                     g2[e] = g1[e]; g1[e] = g0[e]; u2[e] = u1[e]; u1[e] = u0[e];
;                 }
;                 u32x4 w; w.x = cvt_pk_bf16(o[0], o[1]); w.y = cvt_pk_bf16(o[2], o[3]); w.z = cvt_pk_bf16(o[4], o[5]); w.w = cvt_pk_bf16(o[6], o[7]);
;                 *(u32x4*)(Gd + (size_t)(r0 + rb + k) * DFF + c) = w;
;             }
;         }
	v_mul_f32_e32 v81, v74, v50
	v_and_b32_e32 v50, 0xffff0000, v55
	v_pk_fma_f32 v[54:55], v[20:21], v[66:67], v[32:33]
	v_lshlrev_b32_e32 v74, 16, v56
	v_pk_fma_f32 v[54:55], v[24:25], v[58:59], v[54:55]
	v_lshlrev_b32_e32 v75, 16, v52
	v_pk_fma_f32 v[54:55], v[28:29], v[50:51], v[54:55]
	s_nop 0
	v_mul_f32_e32 v66, v55, v55
	v_fmamk_f32 v66, v66, 0xbdd2d3e7, v251
	v_mul_f32_e32 v66, v55, v66
	v_exp_f32_e32 v66, v66
	s_nop 0
	v_add_f32_e32 v66, 1.0, v66
	v_rcp_f32_e32 v66, v66
	s_nop 0
	v_mul_f32_e32 v55, v55, v66
	v_mul_f32_e32 v93, v54, v55
	v_pk_fma_f32 v[54:55], v[108:109], v[96:97], v[112:113]
	s_nop 0
	v_pk_fma_f32 v[54:55], v[116:117], v[84:85], v[54:55]
	s_nop 0
	v_pk_fma_f32 v[54:55], v[120:121], v[74:75], v[54:55]
	s_nop 0
	v_mul_f32_e32 v66, v55, v55
	v_fmamk_f32 v66, v66, 0xbdd2d3e7, v251
	v_mul_f32_e32 v66, v55, v66
	v_exp_f32_e32 v66, v66
	s_nop 0
	v_add_f32_e32 v66, 1.0, v66
	v_rcp_f32_e32 v66, v66
	s_nop 0
	v_mul_f32_e32 v55, v55, v66
	v_pk_fma_f32 v[66:67], v[2:3], v[70:71], v[14:15]
	v_mul_f32_e32 v94, v54, v55
	v_and_b32_e32 v55, 0xffff0000, v52
	v_and_b32_e32 v54, 0xffff0000, v56
	v_pk_fma_f32 v[66:67], v[6:7], v[62:63], v[66:67]
	v_pk_fma_f32 v[70:71], v[122:123], v[90:91], v[126:127]
	v_pk_fma_f32 v[66:67], v[10:11], v[54:55], v[66:67]
	v_pk_fma_f32 v[70:71], v[140:141], v[82:83], v[70:71]
	v_mul_f32_e32 v52, v67, v67
	v_fmamk_f32 v52, v52, 0xbdd2d3e7, v251
	v_mul_f32_e32 v52, v67, v52
	v_exp_f32_e32 v52, v52
	s_nop 0
	v_add_f32_e32 v52, 1.0, v52
	v_rcp_f32_e32 v52, v52
	s_nop 0
	v_mul_f32_e32 v52, v67, v52
	v_mul_f32_e32 v95, v66, v52
	v_lshlrev_b32_e32 v66, 16, v57
	v_lshlrev_b32_e32 v67, 16, v53
	v_pk_fma_f32 v[70:71], v[142:143], v[66:67], v[70:71]
	v_and_b32_e32 v53, 0xffff0000, v53
	v_mul_f32_e32 v52, v71, v71
	v_fmamk_f32 v52, v52, 0xbdd2d3e7, v251
	v_mul_f32_e32 v52, v71, v52
	v_exp_f32_e32 v52, v52
	s_nop 0
	v_add_f32_e32 v52, 1.0, v52
	v_rcp_f32_e32 v52, v52
	s_nop 0
	v_mul_f32_e32 v52, v71, v52
	v_mul_f32_e32 v71, v70, v52
	v_and_b32_e32 v52, 0xffff0000, v57
	v_pk_fma_f32 v[56:57], v[4:5], v[68:69], v[16:17]
	s_nop 0
	v_pk_fma_f32 v[56:57], v[8:9], v[60:61], v[56:57]
	s_nop 0
	v_pk_fma_f32 v[56:57], v[12:13], v[52:53], v[56:57]
	s_nop 0
	v_mul_f32_e32 v68, v57, v57
	v_fmamk_f32 v68, v68, 0xbdd2d3e7, v251
	v_mul_f32_e32 v68, v57, v68
	v_exp_f32_e32 v68, v68
	s_nop 0
	v_add_f32_e32 v68, 1.0, v68
	v_rcp_f32_e32 v68, v68
	s_nop 0
	v_mul_f32_e32 v57, v57, v68
	v_mul_f32_e32 v56, v56, v57
	v_cvt_pk_bf16_f32 v68, v92, v80
	v_cvt_pk_bf16_f32 v69, v81, v93
	v_cvt_pk_bf16_f32 v70, v94, v95
	v_cvt_pk_bf16_f32 v71, v71, v56
	v_mad_i64_i32 v[56:57], s[2:3], v182, s12, v[130:131]
	global_store_dwordx4 v[56:57], v[68:71], off
	v_pk_fma_f32 v[56:57], v[132:133], v[88:89], v[134:135]
	s_nop 0
	v_pk_fma_f32 v[56:57], v[136:137], v[78:79], v[56:57]
	s_nop 0
	v_pk_fma_f32 v[56:57], v[138:139], v[166:167], v[56:57]
	s_nop 0
	v_mul_f32_e32 v68, v57, v57
	v_fmamk_f32 v68, v68, 0xbdd2d3e7, v251
	v_mul_f32_e32 v68, v57, v68
	v_exp_f32_e32 v68, v68
	s_nop 0
	v_add_f32_e32 v68, 1.0, v68
	v_rcp_f32_e32 v68, v68
	s_nop 0
	v_mul_f32_e32 v57, v57, v68
	v_mul_f32_e32 v68, v56, v57
	v_pk_fma_f32 v[56:57], v[18:19], v[72:73], v[30:31]
	s_nop 0
	v_pk_fma_f32 v[56:57], v[22:23], v[64:65], v[56:57]
	s_nop 0
	v_pk_fma_f32 v[56:57], v[26:27], v[164:165], v[56:57]
	s_nop 0
	v_mul_f32_e32 v42, v57, v57
	v_fmamk_f32 v42, v42, 0xbdd2d3e7, v251
	v_mul_f32_e32 v42, v57, v42
	v_exp_f32_e32 v42, v42
	s_nop 0
	v_add_f32_e32 v42, 1.0, v42
	v_rcp_f32_e32 v42, v42
	s_nop 0
	v_mul_f32_e32 v42, v57, v42
	v_mul_f32_e32 v46, v56, v42
	v_pk_fma_f32 v[56:57], v[106:107], v[86:87], v[110:111]
	s_nop 0
	v_pk_fma_f32 v[56:57], v[114:115], v[76:77], v[56:57]
	s_nop 0
	v_pk_fma_f32 v[56:57], v[118:119], v[162:163], v[56:57]
	s_nop 0
	v_mul_f32_e32 v42, v57, v57
	v_fmamk_f32 v42, v42, 0xbdd2d3e7, v251
	v_mul_f32_e32 v42, v57, v42
	v_exp_f32_e32 v42, v42
	s_nop 0
	v_add_f32_e32 v42, 1.0, v42
	v_rcp_f32_e32 v42, v42
	s_nop 0
	v_mul_f32_e32 v42, v57, v42
	v_mul_f32_e32 v56, v56, v42
	v_pk_fma_f32 v[42:43], v[20:21], v[58:59], v[32:33]
	s_nop 0
	v_pk_fma_f32 v[42:43], v[24:25], v[50:51], v[42:43]
	s_nop 0
	v_pk_fma_f32 v[42:43], v[28:29], v[98:99], v[42:43]
	s_nop 0
	v_mul_f32_e32 v47, v43, v43
	v_fmamk_f32 v47, v47, 0xbdd2d3e7, v251
	v_mul_f32_e32 v47, v43, v47
	v_exp_f32_e32 v47, v47
	s_nop 0
	v_add_f32_e32 v47, 1.0, v47
	v_rcp_f32_e32 v47, v47
	s_nop 0
	v_mul_f32_e32 v43, v43, v47
	v_mul_f32_e32 v47, v42, v43
	v_pk_fma_f32 v[42:43], v[108:109], v[84:85], v[112:113]
	s_nop 0
	v_pk_fma_f32 v[42:43], v[116:117], v[74:75], v[42:43]
	s_nop 0
	v_pk_fma_f32 v[42:43], v[120:121], v[160:161], v[42:43]
	s_nop 0
	v_mul_f32_e32 v57, v43, v43
	v_fmamk_f32 v57, v57, 0xbdd2d3e7, v251
	v_mul_f32_e32 v57, v43, v57
	v_exp_f32_e32 v57, v57
	s_nop 0
	v_add_f32_e32 v57, 1.0, v57
	v_rcp_f32_e32 v57, v57
	s_nop 0
	v_mul_f32_e32 v43, v43, v57
	v_mul_f32_e32 v57, v42, v43
	v_pk_fma_f32 v[42:43], v[2:3], v[62:63], v[14:15]
	s_nop 0
	v_pk_fma_f32 v[42:43], v[6:7], v[54:55], v[42:43]
	s_nop 0
	v_pk_fma_f32 v[42:43], v[10:11], v[100:101], v[42:43]
	s_nop 0
	v_mul_f32_e32 v44, v43, v43
	v_fmamk_f32 v44, v44, 0xbdd2d3e7, v251
	v_mul_f32_e32 v44, v43, v44
	v_exp_f32_e32 v44, v44
	s_nop 0
	v_add_f32_e32 v44, 1.0, v44
	v_rcp_f32_e32 v44, v44
	s_nop 0
	v_mul_f32_e32 v43, v43, v44
	v_mul_f32_e32 v44, v42, v43
	v_pk_fma_f32 v[42:43], v[122:123], v[82:83], v[126:127]
	s_nop 0
	v_pk_fma_f32 v[42:43], v[140:141], v[66:67], v[42:43]
	s_nop 0
	v_pk_fma_f32 v[42:43], v[142:143], v[158:159], v[42:43]
	s_nop 0
	v_mul_f32_e32 v48, v43, v43
	v_fmamk_f32 v48, v48, 0xbdd2d3e7, v251
	v_mul_f32_e32 v48, v43, v48
; __device__ __forceinline__ unsigned cvt_pk_bf16(float lo, float hi) { unsigned r; asm volatile("v_cvt_pk_bf16_f32 %0, %1, %2" : "=v"(r) : "v"(lo), "v"(hi)); return r; }
; __device__ __forceinline__ float gelu_tanh(float x) {
;     const float y = 0.7978845608028654f * (x + 0.044715f * x * x * x);
;     return x * __builtin_amdgcn_rcpf(1.0f + __builtin_amdgcn_exp2f(-2.0f * LOG2E * y));
; }
; __device__ __forceinline__ void phase_conv(const Params& p, int layer) {
;     ...
;         for (int rb = 0; rb < RCH; rb += 8) {
;             u32x4 gr[8], ur[8];
; #pragma unroll
;             for (int k = 0; k < 8; ++k) { gr[k] = __builtin_nontemporal_load((const u32x4*)(U + (size_t)(r0 + rb + k) * DFF2 + c)); ur[k] = __builtin_nontemporal_load((const u32x4*)(U + (size_t)(r0 + rb + k) * DFF2 + DFF + c)); }
; #pragma unroll
;             for (int k = 0; k < 8; ++k) {
;                 float g0[8], u0[8]; unpack8(gr[k], g0); unpack8(ur[k], u0);
;                 float o[8];
; #pragma unroll
;                 for (int e = 0; e < 8; ++e) {
;                     const float gp = bg[e] + wg[0][e] * g2[e] + wg[1][e] * g1[e] + wg[2][e] * g0[e];
;                     const float up = bu[e] + wu[0][e] * u2[e] + wu[1][e] * u1[e] + wu[2][e] * u0[e];
;                     o[e] = gelu_tanh(gp) * up;
;                     g2[e] = g1[e]; g1[e] = g0[e]; u2[e] = u1[e]; u1[e] = u0[e];
;                 }
;                 u32x4 w; w.x = cvt_pk_bf16(o[0], o[1]); w.y = cvt_pk_bf16(o[2], o[3]); w.z = cvt_pk_bf16(o[4], o[5]); w.w = cvt_pk_bf16(o[6], o[7]);
;                 *(u32x4*)(Gd + (size_t)(r0 + rb + k) * DFF + c) = w;
;             }
;         }
	v_exp_f32_e32 v48, v48
	s_nop 0
	v_add_f32_e32 v48, 1.0, v48
	v_rcp_f32_e32 v48, v48
	s_nop 0
	v_mul_f32_e32 v43, v43, v48
	v_mul_f32_e32 v48, v42, v43
	v_pk_fma_f32 v[42:43], v[4:5], v[60:61], v[16:17]
	s_nop 0
	v_pk_fma_f32 v[42:43], v[8:9], v[52:53], v[42:43]
	s_nop 0
	v_pk_fma_f32 v[42:43], v[12:13], v[102:103], v[42:43]
	s_nop 0
	v_mul_f32_e32 v45, v43, v43
	v_fmamk_f32 v45, v45, 0xbdd2d3e7, v251
	v_mul_f32_e32 v45, v43, v45
	v_exp_f32_e32 v45, v45
	s_nop 0
	v_add_f32_e32 v45, 1.0, v45
	v_rcp_f32_e32 v45, v45
	s_nop 0
	v_mul_f32_e32 v43, v43, v45
	v_mul_f32_e32 v45, v42, v43
	v_cvt_pk_bf16_f32 v42, v68, v46
	v_cvt_pk_bf16_f32 v43, v56, v47
	v_mad_i64_i32 v[46:47], s[2:3], v181, s12, v[130:131]
	v_cvt_pk_bf16_f32 v44, v57, v44
	v_cvt_pk_bf16_f32 v45, v48, v45
	global_store_dwordx4 v[46:47], v[42:45], off
	s_nop 1
	v_pk_fma_f32 v[42:43], v[132:133], v[78:79], v[134:135]
	s_nop 0
	v_pk_fma_f32 v[42:43], v[136:137], v[166:167], v[42:43]
	s_nop 0
	v_pk_fma_f32 v[42:43], v[138:139], v[156:157], v[42:43]
	s_nop 0
	v_mul_f32_e32 v44, v43, v43
	v_fmamk_f32 v44, v44, 0xbdd2d3e7, v251
	v_mul_f32_e32 v44, v43, v44
	v_exp_f32_e32 v44, v44
	s_nop 0
	v_add_f32_e32 v44, 1.0, v44
	v_rcp_f32_e32 v44, v44
	s_nop 0
	v_mul_f32_e32 v43, v43, v44
	v_mul_f32_e32 v44, v42, v43
	v_pk_fma_f32 v[42:43], v[18:19], v[64:65], v[30:31]
	s_nop 0
	v_pk_fma_f32 v[42:43], v[22:23], v[164:165], v[42:43]
	v_pk_fma_f32 v[164:165], v[18:19], v[164:165], v[30:31]
	v_pk_fma_f32 v[42:43], v[26:27], v[104:105], v[42:43]
	v_pk_fma_f32 v[164:165], v[22:23], v[104:105], v[164:165]
	v_mul_f32_e32 v34, v43, v43
	v_fmamk_f32 v34, v34, 0xbdd2d3e7, v251
	v_mul_f32_e32 v34, v43, v34
	v_exp_f32_e32 v34, v34
	s_nop 0
	v_add_f32_e32 v34, 1.0, v34
	v_rcp_f32_e32 v34, v34
	s_nop 0
	v_mul_f32_e32 v34, v43, v34
	v_mul_f32_e32 v38, v42, v34
	v_pk_fma_f32 v[42:43], v[106:107], v[76:77], v[110:111]
	s_nop 0
	v_pk_fma_f32 v[42:43], v[114:115], v[162:163], v[42:43]
	v_pk_fma_f32 v[162:163], v[106:107], v[162:163], v[110:111]
	v_pk_fma_f32 v[42:43], v[118:119], v[154:155], v[42:43]
	v_pk_fma_f32 v[162:163], v[114:115], v[154:155], v[162:163]
	v_mul_f32_e32 v34, v43, v43
	v_fmamk_f32 v34, v34, 0xbdd2d3e7, v251
	v_mul_f32_e32 v34, v43, v34
	v_exp_f32_e32 v34, v34
	s_nop 0
	v_add_f32_e32 v34, 1.0, v34
	v_rcp_f32_e32 v34, v34
	s_nop 0
	v_mul_f32_e32 v34, v43, v34
	v_mul_f32_e32 v42, v42, v34
	v_pk_fma_f32 v[34:35], v[20:21], v[50:51], v[32:33]
	s_nop 0
	v_pk_fma_f32 v[34:35], v[24:25], v[98:99], v[34:35]
	s_nop 0
	v_pk_fma_f32 v[34:35], v[28:29], v[124:125], v[34:35]
	s_nop 0
	v_mul_f32_e32 v39, v35, v35
	v_fmamk_f32 v39, v39, 0xbdd2d3e7, v251
	v_mul_f32_e32 v39, v35, v39
	v_exp_f32_e32 v39, v39
	s_nop 0
	v_add_f32_e32 v39, 1.0, v39
	v_rcp_f32_e32 v39, v39
	s_nop 0
	v_mul_f32_e32 v35, v35, v39
	v_mul_f32_e32 v39, v34, v35
	v_pk_fma_f32 v[34:35], v[108:109], v[74:75], v[112:113]
	s_nop 0
	v_pk_fma_f32 v[34:35], v[116:117], v[160:161], v[34:35]
	s_nop 0
	v_pk_fma_f32 v[34:35], v[120:121], v[152:153], v[34:35]
	s_nop 0
	v_mul_f32_e32 v43, v35, v35
	v_fmamk_f32 v43, v43, 0xbdd2d3e7, v251
	v_mul_f32_e32 v43, v35, v43
	v_exp_f32_e32 v43, v43
	s_nop 0
	v_add_f32_e32 v43, 1.0, v43
	v_rcp_f32_e32 v43, v43
	s_nop 0
	v_mul_f32_e32 v35, v35, v43
	v_mul_f32_e32 v43, v34, v35
	v_pk_fma_f32 v[34:35], v[2:3], v[54:55], v[14:15]
	s_nop 0
	v_pk_fma_f32 v[34:35], v[6:7], v[100:101], v[34:35]
	s_nop 0
	v_pk_fma_f32 v[34:35], v[10:11], v[128:129], v[34:35]
	s_nop 0
	v_mul_f32_e32 v36, v35, v35
	v_fmamk_f32 v36, v36, 0xbdd2d3e7, v251
	v_mul_f32_e32 v36, v35, v36
	v_exp_f32_e32 v36, v36
	s_nop 0
	v_add_f32_e32 v36, 1.0, v36
	v_rcp_f32_e32 v36, v36
	s_nop 0
	v_mul_f32_e32 v35, v35, v36
	v_mul_f32_e32 v36, v34, v35
	v_pk_fma_f32 v[34:35], v[122:123], v[66:67], v[126:127]
	s_nop 0
	v_pk_fma_f32 v[34:35], v[140:141], v[158:159], v[34:35]
	s_nop 0
	v_pk_fma_f32 v[34:35], v[142:143], v[150:151], v[34:35]
	s_nop 0
	v_mul_f32_e32 v40, v35, v35
	v_fmamk_f32 v40, v40, 0xbdd2d3e7, v251
	v_mul_f32_e32 v40, v35, v40
	v_exp_f32_e32 v40, v40
	s_nop 0
	v_add_f32_e32 v40, 1.0, v40
	v_rcp_f32_e32 v40, v40
	s_nop 0
	v_mul_f32_e32 v35, v35, v40
	v_mul_f32_e32 v40, v34, v35
	v_pk_fma_f32 v[34:35], v[4:5], v[52:53], v[16:17]
	s_nop 0
	v_pk_fma_f32 v[34:35], v[8:9], v[102:103], v[34:35]
	s_nop 0
	v_pk_fma_f32 v[34:35], v[12:13], v[148:149], v[34:35]
	s_nop 0
	v_mul_f32_e32 v37, v35, v35
	v_fmamk_f32 v37, v37, 0xbdd2d3e7, v251
	v_mul_f32_e32 v37, v35, v37
	v_exp_f32_e32 v37, v37
	s_nop 0
	v_add_f32_e32 v37, 1.0, v37
	v_rcp_f32_e32 v37, v37
	s_nop 0
	v_mul_f32_e32 v35, v35, v37
	v_mul_f32_e32 v37, v34, v35
	v_cvt_pk_bf16_f32 v34, v44, v38
	v_cvt_pk_bf16_f32 v35, v42, v39
	v_mad_i64_i32 v[38:39], s[2:3], v180, s12, v[130:131]
	v_cvt_pk_bf16_f32 v36, v43, v36
	v_cvt_pk_bf16_f32 v37, v40, v37
	global_store_dwordx4 v[38:39], v[34:37], off
	s_nop 1
	v_mad_i64_i32 v[34:35], s[2:3], v175, s7, v[146:147]
	v_lshl_add_u64 v[34:35], v[34:35], 0, v[144:145]
	global_load_dwordx4 v[90:93], v[34:35], off nt
	v_add_co_u32_e32 v34, vcc, s6, v34
	s_nop 1
	v_addc_co_u32_e32 v35, vcc, 0, v35, vcc
	global_load_dwordx4 v[94:97], v[34:35], off offset:3072 nt
	v_mad_i64_i32 v[34:35], s[2:3], v174, s7, v[146:147]
	v_lshl_add_u64 v[34:35], v[34:35], 0, v[144:145]
	global_load_dwordx4 v[82:85], v[34:35], off nt
	v_add_co_u32_e32 v34, vcc, s6, v34
	s_nop 1
	v_addc_co_u32_e32 v35, vcc, 0, v35, vcc
	global_load_dwordx4 v[86:89], v[34:35], off offset:3072 nt
	v_mad_i64_i32 v[34:35], s[2:3], v173, s7, v[146:147]
	v_lshl_add_u64 v[34:35], v[34:35], 0, v[144:145]
	global_load_dwordx4 v[74:77], v[34:35], off nt
	v_add_co_u32_e32 v34, vcc, s6, v34
	s_nop 1
	v_addc_co_u32_e32 v35, vcc, 0, v35, vcc
; __device__ __forceinline__ unsigned cvt_pk_bf16(float lo, float hi) { unsigned r; asm volatile("v_cvt_pk_bf16_f32 %0, %1, %2" : "=v"(r) : "v"(lo), "v"(hi)); return r; }
; __device__ __forceinline__ float gelu_tanh(float x) {
;     const float y = 0.7978845608028654f * (x + 0.044715f * x * x * x);
;     return x * __builtin_amdgcn_rcpf(1.0f + __builtin_amdgcn_exp2f(-2.0f * LOG2E * y));
; }
; __device__ __forceinline__ void phase_conv(const Params& p, int layer) {
;     ...
;         for (int rb = 0; rb < RCH; rb += 8) {
;             u32x4 gr[8], ur[8];
; #pragma unroll
;             for (int k = 0; k < 8; ++k) { gr[k] = __builtin_nontemporal_load((const u32x4*)(U + (size_t)(r0 + rb + k) * DFF2 + c)); ur[k] = __builtin_nontemporal_load((const u32x4*)(U + (size_t)(r0 + rb + k) * DFF2 + DFF + c)); }
; #pragma unroll
;             for (int k = 0; k < 8; ++k) {
;                 float g0[8], u0[8]; unpack8(gr[k], g0); unpack8(ur[k], u0);
;                 float o[8];
; #pragma unroll
;                 for (int e = 0; e < 8; ++e) {
;                     const float gp = bg[e] + wg[0][e] * g2[e] + wg[1][e] * g1[e] + wg[2][e] * g0[e];
;                     const float up = bu[e] + wu[0][e] * u2[e] + wu[1][e] * u1[e] + wu[2][e] * u0[e];
;                     o[e] = gelu_tanh(gp) * up;
;                     g2[e] = g1[e]; g1[e] = g0[e]; u2[e] = u1[e]; u1[e] = u0[e];
;                 }
;                 u32x4 w; w.x = cvt_pk_bf16(o[0], o[1]); w.y = cvt_pk_bf16(o[2], o[3]); w.z = cvt_pk_bf16(o[4], o[5]); w.w = cvt_pk_bf16(o[6], o[7]);
;                 *(u32x4*)(Gd + (size_t)(r0 + rb + k) * DFF + c) = w;
;             }
;         }
	global_load_dwordx4 v[78:81], v[34:35], off offset:3072 nt
	v_mad_i64_i32 v[34:35], s[2:3], v172, s7, v[146:147]
	v_lshl_add_u64 v[34:35], v[34:35], 0, v[144:145]
	global_load_dwordx4 v[66:69], v[34:35], off nt
	v_add_co_u32_e32 v34, vcc, s6, v34
	s_nop 1
	v_addc_co_u32_e32 v35, vcc, 0, v35, vcc
	global_load_dwordx4 v[70:73], v[34:35], off offset:3072 nt
	v_mad_i64_i32 v[34:35], s[2:3], v171, s7, v[146:147]
	v_lshl_add_u64 v[34:35], v[34:35], 0, v[144:145]
	global_load_dwordx4 v[58:61], v[34:35], off nt
	v_add_co_u32_e32 v34, vcc, s6, v34
	s_nop 1
	v_addc_co_u32_e32 v35, vcc, 0, v35, vcc
	global_load_dwordx4 v[62:65], v[34:35], off offset:3072 nt
	v_mad_i64_i32 v[34:35], s[2:3], v170, s7, v[146:147]
	v_lshl_add_u64 v[34:35], v[34:35], 0, v[144:145]
	global_load_dwordx4 v[50:53], v[34:35], off nt
	v_add_co_u32_e32 v34, vcc, s6, v34
	s_nop 1
	v_addc_co_u32_e32 v35, vcc, 0, v35, vcc
	global_load_dwordx4 v[54:57], v[34:35], off offset:3072 nt
	v_mad_i64_i32 v[34:35], s[2:3], v169, s7, v[146:147]
	v_lshl_add_u64 v[34:35], v[34:35], 0, v[144:145]
	global_load_dwordx4 v[42:45], v[34:35], off nt
	v_add_co_u32_e32 v34, vcc, s6, v34
	s_nop 1
	v_addc_co_u32_e32 v35, vcc, 0, v35, vcc
	global_load_dwordx4 v[46:49], v[34:35], off offset:3072 nt
	v_mad_i64_i32 v[34:35], s[2:3], v168, s7, v[146:147]
	v_lshl_add_u64 v[38:39], v[34:35], 0, v[144:145]
	v_pk_fma_f32 v[144:145], v[132:133], v[166:167], v[134:135]
	global_load_dwordx4 v[34:37], v[38:39], off nt
	v_pk_fma_f32 v[144:145], v[136:137], v[156:157], v[144:145]
	v_add_co_u32_e32 v38, vcc, s6, v38
	s_waitcnt vmcnt(14)
	v_lshlrev_b32_e32 v147, 16, v90
	v_addc_co_u32_e32 v39, vcc, 0, v39, vcc
	global_load_dwordx4 v[38:41], v[38:39], off offset:3072 nt
	s_waitcnt vmcnt(14)
	v_lshlrev_b32_e32 v146, 16, v94
	v_pk_fma_f32 v[144:145], v[138:139], v[146:147], v[144:145]
	s_nop 0
	v_mul_f32_e32 v166, v145, v145
	v_fmamk_f32 v166, v166, 0xbdd2d3e7, v251
	v_mul_f32_e32 v166, v145, v166
	v_exp_f32_e32 v166, v166
	s_nop 0
	v_add_f32_e32 v166, 1.0, v166
	v_rcp_f32_e32 v166, v166
	s_nop 0
	v_mul_f32_e32 v145, v145, v166
	v_mul_f32_e32 v166, v144, v145
	v_and_b32_e32 v145, 0xffff0000, v90
	v_and_b32_e32 v144, 0xffff0000, v94
	v_pk_fma_f32 v[164:165], v[26:27], v[144:145], v[164:165]
	s_nop 0
	v_mul_f32_e32 v90, v165, v165
	v_fmamk_f32 v90, v90, 0xbdd2d3e7, v251
	v_mul_f32_e32 v90, v165, v90
	v_exp_f32_e32 v90, v90
	s_nop 0
	v_add_f32_e32 v90, 1.0, v90
	v_rcp_f32_e32 v90, v90
	s_nop 0
	v_mul_f32_e32 v90, v165, v90
	v_mul_f32_e32 v167, v164, v90
	v_lshlrev_b32_e32 v164, 16, v95
	v_lshlrev_b32_e32 v165, 16, v91
	v_pk_fma_f32 v[162:163], v[118:119], v[164:165], v[162:163]
	v_and_b32_e32 v91, 0xffff0000, v91
	v_mul_f32_e32 v90, v163, v163
	v_fmamk_f32 v90, v90, 0xbdd2d3e7, v251
	v_mul_f32_e32 v90, v163, v90
	v_exp_f32_e32 v90, v90
	s_nop 0
	v_add_f32_e32 v90, 1.0, v90
	v_rcp_f32_e32 v90, v90
	s_nop 0
	v_mul_f32_e32 v90, v163, v90
	v_mul_f32_e32 v176, v162, v90
	v_and_b32_e32 v90, 0xffff0000, v95
	v_pk_fma_f32 v[94:95], v[20:21], v[98:99], v[32:33]
	v_lshlrev_b32_e32 v162, 16, v96
	v_pk_fma_f32 v[94:95], v[24:25], v[124:125], v[94:95]
	v_lshlrev_b32_e32 v163, 16, v92
	v_pk_fma_f32 v[94:95], v[28:29], v[90:91], v[94:95]
	s_nop 0
	v_mul_f32_e32 v98, v95, v95
	v_fmamk_f32 v98, v98, 0xbdd2d3e7, v251
	v_mul_f32_e32 v98, v95, v98
	v_exp_f32_e32 v98, v98
	s_nop 0
	v_add_f32_e32 v98, 1.0, v98
	v_rcp_f32_e32 v98, v98
	s_nop 0
	v_mul_f32_e32 v95, v95, v98
	v_mul_f32_e32 v177, v94, v95
	v_pk_fma_f32 v[94:95], v[108:109], v[160:161], v[112:113]
	s_nop 0
	v_pk_fma_f32 v[94:95], v[116:117], v[152:153], v[94:95]
	s_nop 0
	v_pk_fma_f32 v[94:95], v[120:121], v[162:163], v[94:95]
	s_nop 0
	v_mul_f32_e32 v98, v95, v95
	v_fmamk_f32 v98, v98, 0xbdd2d3e7, v251
	v_mul_f32_e32 v98, v95, v98
	v_exp_f32_e32 v98, v98
	s_nop 0
	v_add_f32_e32 v98, 1.0, v98
	v_rcp_f32_e32 v98, v98
	s_nop 0
	v_mul_f32_e32 v95, v95, v98
	v_pk_fma_f32 v[98:99], v[2:3], v[100:101], v[14:15]
	v_mul_f32_e32 v160, v94, v95
	v_and_b32_e32 v95, 0xffff0000, v92
	v_and_b32_e32 v94, 0xffff0000, v96
	v_pk_fma_f32 v[98:99], v[6:7], v[128:129], v[98:99]
	v_pk_fma_f32 v[100:101], v[122:123], v[158:159], v[126:127]
	v_pk_fma_f32 v[98:99], v[10:11], v[94:95], v[98:99]
	v_pk_fma_f32 v[100:101], v[140:141], v[150:151], v[100:101]
	v_mul_f32_e32 v92, v99, v99
	v_fmamk_f32 v92, v92, 0xbdd2d3e7, v251
	v_mul_f32_e32 v92, v99, v92
	v_exp_f32_e32 v92, v92
	s_waitcnt vmcnt(13)
	v_lshlrev_b32_e32 v159, 16, v82
	v_add_f32_e32 v92, 1.0, v92
	v_rcp_f32_e32 v92, v92
	s_nop 0
	v_mul_f32_e32 v92, v99, v92
	v_mul_f32_e32 v161, v98, v92
	v_lshlrev_b32_e32 v98, 16, v97
	v_lshlrev_b32_e32 v99, 16, v93
	v_pk_fma_f32 v[100:101], v[142:143], v[98:99], v[100:101]
	v_and_b32_e32 v93, 0xffff0000, v93
	v_mul_f32_e32 v92, v101, v101
	v_fmamk_f32 v92, v92, 0xbdd2d3e7, v251
	v_mul_f32_e32 v92, v101, v92
	v_exp_f32_e32 v92, v92
	s_nop 0
	v_add_f32_e32 v92, 1.0, v92
	v_rcp_f32_e32 v92, v92
	s_nop 0
	v_mul_f32_e32 v92, v101, v92
	v_mul_f32_e32 v158, v100, v92
	v_and_b32_e32 v92, 0xffff0000, v97
	v_pk_fma_f32 v[96:97], v[4:5], v[102:103], v[16:17]
	s_nop 0
	v_pk_fma_f32 v[96:97], v[8:9], v[148:149], v[96:97]
	s_nop 0
	v_pk_fma_f32 v[96:97], v[12:13], v[92:93], v[96:97]
	s_nop 0
	v_mul_f32_e32 v100, v97, v97
	v_fmamk_f32 v100, v100, 0xbdd2d3e7, v251
	v_mul_f32_e32 v100, v97, v100
	v_exp_f32_e32 v100, v100
	s_nop 0
	v_add_f32_e32 v100, 1.0, v100
	v_rcp_f32_e32 v100, v100
	s_nop 0
	v_mul_f32_e32 v97, v97, v100
	v_mul_f32_e32 v96, v96, v97
	v_cvt_pk_bf16_f32 v100, v166, v167
	v_cvt_pk_bf16_f32 v101, v176, v177
	v_cvt_pk_bf16_f32 v102, v160, v161
	v_cvt_pk_bf16_f32 v103, v158, v96
	v_mad_i64_i32 v[96:97], s[2:3], v175, s12, v[130:131]
	global_store_dwordx4 v[96:97], v[100:103], off
	v_pk_fma_f32 v[96:97], v[132:133], v[156:157], v[134:135]
	s_waitcnt vmcnt(13)
; __device__ __forceinline__ unsigned cvt_pk_bf16(float lo, float hi) { unsigned r; asm volatile("v_cvt_pk_bf16_f32 %0, %1, %2" : "=v"(r) : "v"(lo), "v"(hi)); return r; }
; __device__ __forceinline__ float gelu_tanh(float x) {
;     const float y = 0.7978845608028654f * (x + 0.044715f * x * x * x);
;     return x * __builtin_amdgcn_rcpf(1.0f + __builtin_amdgcn_exp2f(-2.0f * LOG2E * y));
; }
; __device__ __forceinline__ void phase_conv(const Params& p, int layer) {
;     ...
;         for (int rb = 0; rb < RCH; rb += 8) {
;             u32x4 gr[8], ur[8];
; #pragma unroll
;             for (int k = 0; k < 8; ++k) { gr[k] = __builtin_nontemporal_load((const u32x4*)(U + (size_t)(r0 + rb + k) * DFF2 + c)); ur[k] = __builtin_nontemporal_load((const u32x4*)(U + (size_t)(r0 + rb + k) * DFF2 + DFF + c)); }
; #pragma unroll
;             for (int k = 0; k < 8; ++k) {
;                 float g0[8], u0[8]; unpack8(gr[k], g0); unpack8(ur[k], u0);
;                 float o[8];
; #pragma unroll
;                 for (int e = 0; e < 8; ++e) {
;                     const float gp = bg[e] + wg[0][e] * g2[e] + wg[1][e] * g1[e] + wg[2][e] * g0[e];
;                     const float up = bu[e] + wu[0][e] * u2[e] + wu[1][e] * u1[e] + wu[2][e] * u0[e];
;                     o[e] = gelu_tanh(gp) * up;
;                     g2[e] = g1[e]; g1[e] = g0[e]; u2[e] = u1[e]; u1[e] = u0[e];
;                 }
;                 u32x4 w; w.x = cvt_pk_bf16(o[0], o[1]); w.y = cvt_pk_bf16(o[2], o[3]); w.z = cvt_pk_bf16(o[4], o[5]); w.w = cvt_pk_bf16(o[6], o[7]);
;                 *(u32x4*)(Gd + (size_t)(r0 + rb + k) * DFF + c) = w;
;             }
;         }
	v_lshlrev_b32_e32 v158, 16, v86
	v_pk_fma_f32 v[96:97], v[136:137], v[146:147], v[96:97]
	v_lshlrev_b32_e32 v156, 16, v87
	v_pk_fma_f32 v[96:97], v[138:139], v[158:159], v[96:97]
	v_lshlrev_b32_e32 v157, 16, v83
	v_mul_f32_e32 v100, v97, v97
	v_fmamk_f32 v100, v100, 0xbdd2d3e7, v251
	v_mul_f32_e32 v100, v97, v100
	v_exp_f32_e32 v100, v100
	v_and_b32_e32 v83, 0xffff0000, v83
	v_add_f32_e32 v100, 1.0, v100
	v_rcp_f32_e32 v100, v100
	s_nop 0
	v_mul_f32_e32 v97, v97, v100
	v_pk_fma_f32 v[100:101], v[18:19], v[104:105], v[30:31]
	v_mul_f32_e32 v102, v96, v97
	v_and_b32_e32 v97, 0xffff0000, v82
	v_and_b32_e32 v96, 0xffff0000, v86
	v_pk_fma_f32 v[100:101], v[22:23], v[144:145], v[100:101]
	s_nop 0
	v_pk_fma_f32 v[100:101], v[26:27], v[96:97], v[100:101]
	s_nop 0
	v_mul_f32_e32 v82, v101, v101
	v_fmamk_f32 v82, v82, 0xbdd2d3e7, v251
	v_mul_f32_e32 v82, v101, v82
	v_exp_f32_e32 v82, v82
	s_nop 0
	v_add_f32_e32 v82, 1.0, v82
	v_rcp_f32_e32 v82, v82
	s_nop 0
	v_mul_f32_e32 v82, v101, v82
	v_mul_f32_e32 v103, v100, v82
	v_pk_fma_f32 v[100:101], v[106:107], v[154:155], v[110:111]
	v_lshlrev_b32_e32 v154, 16, v88
	v_pk_fma_f32 v[100:101], v[114:115], v[164:165], v[100:101]
	v_lshlrev_b32_e32 v155, 16, v84
	v_pk_fma_f32 v[100:101], v[118:119], v[156:157], v[100:101]
	s_nop 0
	v_mul_f32_e32 v82, v101, v101
	v_fmamk_f32 v82, v82, 0xbdd2d3e7, v251
	v_mul_f32_e32 v82, v101, v82
	v_exp_f32_e32 v82, v82
	s_nop 0
	v_add_f32_e32 v82, 1.0, v82
	v_rcp_f32_e32 v82, v82
	s_nop 0
	v_mul_f32_e32 v82, v101, v82
	v_mul_f32_e32 v104, v100, v82
	v_and_b32_e32 v82, 0xffff0000, v87
	v_pk_fma_f32 v[86:87], v[20:21], v[124:125], v[32:33]
	s_nop 0
	v_pk_fma_f32 v[86:87], v[24:25], v[90:91], v[86:87]
	s_nop 0
	v_pk_fma_f32 v[86:87], v[28:29], v[82:83], v[86:87]
	s_nop 0
	v_mul_f32_e32 v100, v87, v87
	v_fmamk_f32 v100, v100, 0xbdd2d3e7, v251
	v_mul_f32_e32 v100, v87, v100
	v_exp_f32_e32 v100, v100
	s_nop 0
	v_add_f32_e32 v100, 1.0, v100
	v_rcp_f32_e32 v100, v100
	s_nop 0
	v_mul_f32_e32 v87, v87, v100
	v_mul_f32_e32 v105, v86, v87
	v_pk_fma_f32 v[86:87], v[108:109], v[152:153], v[112:113]
	s_nop 0
	v_pk_fma_f32 v[86:87], v[116:117], v[162:163], v[86:87]
	s_nop 0
	v_pk_fma_f32 v[86:87], v[120:121], v[154:155], v[86:87]
	s_nop 0
	v_mul_f32_e32 v100, v87, v87
	v_fmamk_f32 v100, v100, 0xbdd2d3e7, v251
	v_mul_f32_e32 v100, v87, v100
	v_exp_f32_e32 v100, v100
	s_nop 0
	v_add_f32_e32 v100, 1.0, v100
	v_rcp_f32_e32 v100, v100
	s_nop 0
	v_mul_f32_e32 v87, v87, v100
	v_pk_fma_f32 v[100:101], v[2:3], v[128:129], v[14:15]
	v_mul_f32_e32 v124, v86, v87
	v_and_b32_e32 v87, 0xffff0000, v84
	v_and_b32_e32 v86, 0xffff0000, v88
	v_pk_fma_f32 v[100:101], v[6:7], v[94:95], v[100:101]
	v_lshlrev_b32_e32 v128, 16, v89
	v_pk_fma_f32 v[100:101], v[10:11], v[86:87], v[100:101]
	v_lshlrev_b32_e32 v129, 16, v85
	v_mul_f32_e32 v84, v101, v101
	v_fmamk_f32 v84, v84, 0xbdd2d3e7, v251
	v_mul_f32_e32 v84, v101, v84
	v_exp_f32_e32 v84, v84
	v_and_b32_e32 v85, 0xffff0000, v85
	v_add_f32_e32 v84, 1.0, v84
	v_rcp_f32_e32 v84, v84
	s_nop 0
	v_mul_f32_e32 v84, v101, v84
	v_mul_f32_e32 v125, v100, v84
	v_pk_fma_f32 v[100:101], v[122:123], v[150:151], v[126:127]
	s_nop 0
	v_pk_fma_f32 v[100:101], v[140:141], v[98:99], v[100:101]
	s_nop 0
	v_pk_fma_f32 v[100:101], v[142:143], v[128:129], v[100:101]
	s_nop 0
	v_mul_f32_e32 v84, v101, v101
	v_fmamk_f32 v84, v84, 0xbdd2d3e7, v251
	v_mul_f32_e32 v84, v101, v84
	v_exp_f32_e32 v84, v84
	s_nop 0
	v_add_f32_e32 v84, 1.0, v84
	v_rcp_f32_e32 v84, v84
	s_nop 0
	v_mul_f32_e32 v84, v101, v84
	v_mul_f32_e32 v150, v100, v84
	v_and_b32_e32 v84, 0xffff0000, v89
	v_pk_fma_f32 v[88:89], v[4:5], v[148:149], v[16:17]
	s_nop 0
	v_pk_fma_f32 v[88:89], v[8:9], v[92:93], v[88:89]
	s_nop 0
	v_pk_fma_f32 v[88:89], v[12:13], v[84:85], v[88:89]
	s_nop 0
	v_mul_f32_e32 v100, v89, v89
	v_fmamk_f32 v100, v100, 0xbdd2d3e7, v251
	v_mul_f32_e32 v100, v89, v100
	v_exp_f32_e32 v100, v100
	s_nop 0
	v_add_f32_e32 v100, 1.0, v100
	v_rcp_f32_e32 v100, v100
	s_nop 0
	v_mul_f32_e32 v89, v89, v100
	v_mul_f32_e32 v88, v88, v89
	v_cvt_pk_bf16_f32 v100, v102, v103
	v_cvt_pk_bf16_f32 v101, v104, v105
	v_cvt_pk_bf16_f32 v102, v124, v125
	v_cvt_pk_bf16_f32 v103, v150, v88
	v_mad_i64_i32 v[88:89], s[2:3], v174, s12, v[130:131]
	global_store_dwordx4 v[88:89], v[100:103], off
	v_pk_fma_f32 v[88:89], v[132:133], v[146:147], v[134:135]
	s_waitcnt vmcnt(12)
; __device__ __forceinline__ unsigned cvt_pk_bf16(float lo, float hi) { unsigned r; asm volatile("v_cvt_pk_bf16_f32 %0, %1, %2" : "=v"(r) : "v"(lo), "v"(hi)); return r; }
; __device__ __forceinline__ float gelu_tanh(float x) {
;     const float y = 0.7978845608028654f * (x + 0.044715f * x * x * x);
;     return x * __builtin_amdgcn_rcpf(1.0f + __builtin_amdgcn_exp2f(-2.0f * LOG2E * y));
; }
; __device__ __forceinline__ void phase_conv(const Params& p, int layer) {
;     ...
;         for (int rb = 0; rb < RCH; rb += 8) {
;             u32x4 gr[8], ur[8];
; #pragma unroll
;             for (int k = 0; k < 8; ++k) { gr[k] = __builtin_nontemporal_load((const u32x4*)(U + (size_t)(r0 + rb + k) * DFF2 + c)); ur[k] = __builtin_nontemporal_load((const u32x4*)(U + (size_t)(r0 + rb + k) * DFF2 + DFF + c)); }
; #pragma unroll
;             for (int k = 0; k < 8; ++k) {
;                 float g0[8], u0[8]; unpack8(gr[k], g0); unpack8(ur[k], u0);
;                 float o[8];
; #pragma unroll
;                 for (int e = 0; e < 8; ++e) {
;                     const float gp = bg[e] + wg[0][e] * g2[e] + wg[1][e] * g1[e] + wg[2][e] * g0[e];
;                     const float up = bu[e] + wu[0][e] * u2[e] + wu[1][e] * u1[e] + wu[2][e] * u0[e];
;                     o[e] = gelu_tanh(gp) * up;
;                     g2[e] = g1[e]; g1[e] = g0[e]; u2[e] = u1[e]; u1[e] = u0[e];
;                 }
;                 u32x4 w; w.x = cvt_pk_bf16(o[0], o[1]); w.y = cvt_pk_bf16(o[2], o[3]); w.z = cvt_pk_bf16(o[4], o[5]); w.w = cvt_pk_bf16(o[6], o[7]);
;                 *(u32x4*)(Gd + (size_t)(r0 + rb + k) * DFF + c) = w;
;             }
;         }
	v_lshlrev_b32_e32 v124, 16, v78
	v_lshlrev_b32_e32 v125, 16, v74
	v_pk_fma_f32 v[88:89], v[136:137], v[158:159], v[88:89]
	v_lshlrev_b32_e32 v104, 16, v79
	v_pk_fma_f32 v[88:89], v[138:139], v[124:125], v[88:89]
	v_lshlrev_b32_e32 v105, 16, v75
	v_mul_f32_e32 v100, v89, v89
	v_fmamk_f32 v100, v100, 0xbdd2d3e7, v251
	v_mul_f32_e32 v100, v89, v100
	v_exp_f32_e32 v100, v100
	v_and_b32_e32 v75, 0xffff0000, v75
	v_lshlrev_b32_e32 v102, 16, v80
	v_lshlrev_b32_e32 v103, 16, v76
	v_add_f32_e32 v100, 1.0, v100
	v_rcp_f32_e32 v100, v100
	s_nop 0
	v_mul_f32_e32 v89, v89, v100
	v_pk_fma_f32 v[100:101], v[18:19], v[144:145], v[30:31]
	v_mul_f32_e32 v146, v88, v89
	v_and_b32_e32 v89, 0xffff0000, v74
	v_and_b32_e32 v88, 0xffff0000, v78
	v_pk_fma_f32 v[100:101], v[22:23], v[96:97], v[100:101]
	s_nop 0
	v_pk_fma_f32 v[100:101], v[26:27], v[88:89], v[100:101]
	s_nop 0
	v_mul_f32_e32 v74, v101, v101
	v_fmamk_f32 v74, v74, 0xbdd2d3e7, v251
	v_mul_f32_e32 v74, v101, v74
	v_exp_f32_e32 v74, v74
	s_nop 0
	v_add_f32_e32 v74, 1.0, v74
	v_rcp_f32_e32 v74, v74
	s_nop 0
	v_mul_f32_e32 v74, v101, v74
	v_mul_f32_e32 v144, v100, v74
	v_pk_fma_f32 v[100:101], v[106:107], v[164:165], v[110:111]
	s_nop 0
	v_pk_fma_f32 v[100:101], v[114:115], v[156:157], v[100:101]
	s_nop 0
	v_pk_fma_f32 v[100:101], v[118:119], v[104:105], v[100:101]
	s_nop 0
	v_mul_f32_e32 v74, v101, v101
	v_fmamk_f32 v74, v74, 0xbdd2d3e7, v251
	v_mul_f32_e32 v74, v101, v74
	v_exp_f32_e32 v74, v74
	s_nop 0
	v_add_f32_e32 v74, 1.0, v74
	v_rcp_f32_e32 v74, v74
	s_nop 0
	v_mul_f32_e32 v74, v101, v74
	v_mul_f32_e32 v145, v100, v74
	v_and_b32_e32 v74, 0xffff0000, v79
	v_pk_fma_f32 v[78:79], v[20:21], v[90:91], v[32:33]
	v_lshlrev_b32_e32 v100, 16, v81
	v_pk_fma_f32 v[78:79], v[24:25], v[82:83], v[78:79]
	v_lshlrev_b32_e32 v101, 16, v77
	v_pk_fma_f32 v[78:79], v[28:29], v[74:75], v[78:79]
	v_and_b32_e32 v77, 0xffff0000, v77
	v_mul_f32_e32 v90, v79, v79
	v_fmamk_f32 v90, v90, 0xbdd2d3e7, v251
	v_mul_f32_e32 v90, v79, v90
	v_exp_f32_e32 v90, v90
	s_nop 0
	v_add_f32_e32 v90, 1.0, v90
	v_rcp_f32_e32 v90, v90
	s_nop 0
	v_mul_f32_e32 v79, v79, v90
	v_mul_f32_e32 v147, v78, v79
	v_pk_fma_f32 v[78:79], v[108:109], v[162:163], v[112:113]
	s_nop 0
	v_pk_fma_f32 v[78:79], v[116:117], v[154:155], v[78:79]
	s_nop 0
	v_pk_fma_f32 v[78:79], v[120:121], v[102:103], v[78:79]
	s_nop 0
	v_mul_f32_e32 v90, v79, v79
	v_fmamk_f32 v90, v90, 0xbdd2d3e7, v251
	v_mul_f32_e32 v90, v79, v90
	v_exp_f32_e32 v90, v90
	s_nop 0
	v_add_f32_e32 v90, 1.0, v90
	v_rcp_f32_e32 v90, v90
	s_nop 0
	v_mul_f32_e32 v79, v79, v90
	v_pk_fma_f32 v[90:91], v[2:3], v[94:95], v[14:15]
	v_mul_f32_e32 v148, v78, v79
	v_and_b32_e32 v79, 0xffff0000, v76
	v_and_b32_e32 v78, 0xffff0000, v80
	v_pk_fma_f32 v[90:91], v[6:7], v[86:87], v[90:91]
	s_nop 0
	v_pk_fma_f32 v[90:91], v[10:11], v[78:79], v[90:91]
	s_nop 0
	v_mul_f32_e32 v76, v91, v91
	v_fmamk_f32 v76, v76, 0xbdd2d3e7, v251
	v_mul_f32_e32 v76, v91, v76
	v_exp_f32_e32 v76, v76
	s_nop 0
	v_add_f32_e32 v76, 1.0, v76
	v_rcp_f32_e32 v76, v76
	s_nop 0
	v_mul_f32_e32 v76, v91, v76
	v_mul_f32_e32 v94, v90, v76
	v_pk_fma_f32 v[90:91], v[122:123], v[98:99], v[126:127]
	s_waitcnt vmcnt(10)
	v_lshlrev_b32_e32 v98, 16, v70
	v_pk_fma_f32 v[90:91], v[140:141], v[128:129], v[90:91]
	v_lshlrev_b32_e32 v99, 16, v66
	v_pk_fma_f32 v[90:91], v[142:143], v[100:101], v[90:91]
	s_nop 0
	v_mul_f32_e32 v76, v91, v91
	v_fmamk_f32 v76, v76, 0xbdd2d3e7, v251
	v_mul_f32_e32 v76, v91, v76
	v_exp_f32_e32 v76, v76
	s_nop 0
	v_add_f32_e32 v76, 1.0, v76
	v_rcp_f32_e32 v76, v76
	s_nop 0
	v_mul_f32_e32 v76, v91, v76
	v_mul_f32_e32 v95, v90, v76
	v_and_b32_e32 v76, 0xffff0000, v81
	v_pk_fma_f32 v[80:81], v[4:5], v[92:93], v[16:17]
	s_nop 0
	v_pk_fma_f32 v[80:81], v[8:9], v[84:85], v[80:81]
	s_nop 0
	v_pk_fma_f32 v[80:81], v[12:13], v[76:77], v[80:81]
	s_nop 0
	v_mul_f32_e32 v90, v81, v81
	v_fmamk_f32 v90, v90, 0xbdd2d3e7, v251
	v_mul_f32_e32 v90, v81, v90
	v_exp_f32_e32 v90, v90
	s_nop 0
	v_add_f32_e32 v90, 1.0, v90
	v_rcp_f32_e32 v90, v90
	s_nop 0
	v_mul_f32_e32 v81, v81, v90
	v_mul_f32_e32 v80, v80, v81
	v_cvt_pk_bf16_f32 v90, v146, v144
	v_cvt_pk_bf16_f32 v91, v145, v147
	v_cvt_pk_bf16_f32 v92, v148, v94
	v_cvt_pk_bf16_f32 v93, v95, v80
	v_mad_i64_i32 v[80:81], s[2:3], v173, s12, v[130:131]
	global_store_dwordx4 v[80:81], v[90:93], off
	v_pk_fma_f32 v[80:81], v[132:133], v[158:159], v[134:135]
	v_lshlrev_b32_e32 v94, 16, v72
	v_pk_fma_f32 v[80:81], v[136:137], v[124:125], v[80:81]
	v_lshlrev_b32_e32 v95, 16, v68
	v_pk_fma_f32 v[80:81], v[138:139], v[98:99], v[80:81]
	v_lshlrev_b32_e32 v92, 16, v73
	v_mul_f32_e32 v90, v81, v81
	v_fmamk_f32 v90, v90, 0xbdd2d3e7, v251
	v_mul_f32_e32 v90, v81, v90
	v_exp_f32_e32 v90, v90
	v_lshlrev_b32_e32 v93, 16, v69
	v_and_b32_e32 v69, 0xffff0000, v69
	v_add_f32_e32 v90, 1.0, v90
	v_rcp_f32_e32 v90, v90
	s_nop 0
	v_mul_f32_e32 v81, v81, v90
	v_pk_fma_f32 v[90:91], v[18:19], v[96:97], v[30:31]
	v_mul_f32_e32 v144, v80, v81
	v_and_b32_e32 v81, 0xffff0000, v66
	v_and_b32_e32 v80, 0xffff0000, v70
	v_pk_fma_f32 v[90:91], v[22:23], v[88:89], v[90:91]
	v_lshlrev_b32_e32 v96, 16, v71
	v_pk_fma_f32 v[90:91], v[26:27], v[80:81], v[90:91]
	v_lshlrev_b32_e32 v97, 16, v67
	v_mul_f32_e32 v66, v91, v91
	v_fmamk_f32 v66, v66, 0xbdd2d3e7, v251
	v_mul_f32_e32 v66, v91, v66
	v_exp_f32_e32 v66, v66
	v_and_b32_e32 v67, 0xffff0000, v67
	v_add_f32_e32 v66, 1.0, v66
	v_rcp_f32_e32 v66, v66
	s_nop 0
	v_mul_f32_e32 v66, v91, v66
	v_mul_f32_e32 v145, v90, v66
	v_pk_fma_f32 v[90:91], v[106:107], v[156:157], v[110:111]
	s_nop 0
	v_pk_fma_f32 v[90:91], v[114:115], v[104:105], v[90:91]
	s_nop 0
	v_pk_fma_f32 v[90:91], v[118:119], v[96:97], v[90:91]
; __device__ __forceinline__ unsigned cvt_pk_bf16(float lo, float hi) { unsigned r; asm volatile("v_cvt_pk_bf16_f32 %0, %1, %2" : "=v"(r) : "v"(lo), "v"(hi)); return r; }
; __device__ __forceinline__ float gelu_tanh(float x) {
;     const float y = 0.7978845608028654f * (x + 0.044715f * x * x * x);
;     return x * __builtin_amdgcn_rcpf(1.0f + __builtin_amdgcn_exp2f(-2.0f * LOG2E * y));
; }
; __device__ __forceinline__ void phase_conv(const Params& p, int layer) {
;     ...
;         for (int rb = 0; rb < RCH; rb += 8) {
;             u32x4 gr[8], ur[8];
; #pragma unroll
;             for (int k = 0; k < 8; ++k) { gr[k] = __builtin_nontemporal_load((const u32x4*)(U + (size_t)(r0 + rb + k) * DFF2 + c)); ur[k] = __builtin_nontemporal_load((const u32x4*)(U + (size_t)(r0 + rb + k) * DFF2 + DFF + c)); }
; #pragma unroll
;             for (int k = 0; k < 8; ++k) {
;                 float g0[8], u0[8]; unpack8(gr[k], g0); unpack8(ur[k], u0);
;                 float o[8];
; #pragma unroll
;                 for (int e = 0; e < 8; ++e) {
;                     const float gp = bg[e] + wg[0][e] * g2[e] + wg[1][e] * g1[e] + wg[2][e] * g0[e];
;                     const float up = bu[e] + wu[0][e] * u2[e] + wu[1][e] * u1[e] + wu[2][e] * u0[e];
;                     o[e] = gelu_tanh(gp) * up;
;                     g2[e] = g1[e]; g1[e] = g0[e]; u2[e] = u1[e]; u1[e] = u0[e];
;                 }
;                 u32x4 w; w.x = cvt_pk_bf16(o[0], o[1]); w.y = cvt_pk_bf16(o[2], o[3]); w.z = cvt_pk_bf16(o[4], o[5]); w.w = cvt_pk_bf16(o[6], o[7]);
;                 *(u32x4*)(Gd + (size_t)(r0 + rb + k) * DFF + c) = w;
;             }
;         }
	s_nop 0
	v_mul_f32_e32 v66, v91, v91
	v_fmamk_f32 v66, v66, 0xbdd2d3e7, v251
	v_mul_f32_e32 v66, v91, v66
	v_exp_f32_e32 v66, v66
	s_nop 0
	v_add_f32_e32 v66, 1.0, v66
	v_rcp_f32_e32 v66, v66
	s_nop 0
	v_mul_f32_e32 v66, v91, v66
	v_mul_f32_e32 v90, v90, v66
	v_and_b32_e32 v66, 0xffff0000, v71
	v_pk_fma_f32 v[70:71], v[20:21], v[82:83], v[32:33]
	s_nop 0
	v_pk_fma_f32 v[70:71], v[24:25], v[74:75], v[70:71]
	s_nop 0
	v_pk_fma_f32 v[70:71], v[28:29], v[66:67], v[70:71]
	s_nop 0
	v_mul_f32_e32 v82, v71, v71
	v_fmamk_f32 v82, v82, 0xbdd2d3e7, v251
	v_mul_f32_e32 v82, v71, v82
	v_exp_f32_e32 v82, v82
	s_nop 0
	v_add_f32_e32 v82, 1.0, v82
	v_rcp_f32_e32 v82, v82
	s_nop 0
	v_mul_f32_e32 v71, v71, v82
	v_mul_f32_e32 v91, v70, v71
	v_pk_fma_f32 v[70:71], v[108:109], v[154:155], v[112:113]
	s_nop 0
	v_pk_fma_f32 v[70:71], v[116:117], v[102:103], v[70:71]
	s_nop 0
	v_pk_fma_f32 v[70:71], v[120:121], v[94:95], v[70:71]
	s_nop 0
	v_mul_f32_e32 v82, v71, v71
	v_fmamk_f32 v82, v82, 0xbdd2d3e7, v251
	v_mul_f32_e32 v82, v71, v82
	v_exp_f32_e32 v82, v82
	s_nop 0
	v_add_f32_e32 v82, 1.0, v82
	v_rcp_f32_e32 v82, v82
	s_nop 0
	v_mul_f32_e32 v71, v71, v82
	v_pk_fma_f32 v[82:83], v[2:3], v[86:87], v[14:15]
	v_mul_f32_e32 v146, v70, v71
	v_and_b32_e32 v71, 0xffff0000, v68
	v_and_b32_e32 v70, 0xffff0000, v72
	v_pk_fma_f32 v[82:83], v[6:7], v[78:79], v[82:83]
	s_nop 0
	v_pk_fma_f32 v[82:83], v[10:11], v[70:71], v[82:83]
	s_nop 0
	v_mul_f32_e32 v68, v83, v83
	v_fmamk_f32 v68, v68, 0xbdd2d3e7, v251
	v_mul_f32_e32 v68, v83, v68
	v_exp_f32_e32 v68, v68
	s_nop 0
	v_add_f32_e32 v68, 1.0, v68
	v_rcp_f32_e32 v68, v68
	s_nop 0
	v_mul_f32_e32 v68, v83, v68
	v_mul_f32_e32 v86, v82, v68
	v_pk_fma_f32 v[82:83], v[122:123], v[128:129], v[126:127]
	s_nop 0
	v_pk_fma_f32 v[82:83], v[140:141], v[100:101], v[82:83]
	s_nop 0
	v_pk_fma_f32 v[82:83], v[142:143], v[92:93], v[82:83]
	s_nop 0
	v_mul_f32_e32 v68, v83, v83
	v_fmamk_f32 v68, v68, 0xbdd2d3e7, v251
	v_mul_f32_e32 v68, v83, v68
	v_exp_f32_e32 v68, v68
	s_nop 0
	v_add_f32_e32 v68, 1.0, v68
	v_rcp_f32_e32 v68, v68
	s_nop 0
	v_mul_f32_e32 v68, v83, v68
	v_mul_f32_e32 v87, v82, v68
	v_and_b32_e32 v68, 0xffff0000, v73
	v_pk_fma_f32 v[72:73], v[4:5], v[84:85], v[16:17]
	s_nop 0
	v_pk_fma_f32 v[72:73], v[8:9], v[76:77], v[72:73]
	s_nop 0
	v_pk_fma_f32 v[72:73], v[12:13], v[68:69], v[72:73]
	s_nop 0
	v_mul_f32_e32 v82, v73, v73
	v_fmamk_f32 v82, v82, 0xbdd2d3e7, v251
	v_mul_f32_e32 v82, v73, v82
	v_exp_f32_e32 v82, v82
	s_nop 0
	v_add_f32_e32 v82, 1.0, v82
	v_rcp_f32_e32 v82, v82
	s_nop 0
	v_mul_f32_e32 v73, v73, v82
	v_mul_f32_e32 v72, v72, v73
	v_cvt_pk_bf16_f32 v82, v144, v145
	v_cvt_pk_bf16_f32 v83, v90, v91
	v_cvt_pk_bf16_f32 v84, v146, v86
	v_cvt_pk_bf16_f32 v85, v87, v72
	v_mad_i64_i32 v[72:73], s[2:3], v172, s12, v[130:131]
	global_store_dwordx4 v[72:73], v[82:85], off
	v_pk_fma_f32 v[72:73], v[132:133], v[124:125], v[134:135]
	s_waitcnt vmcnt(10)
	v_lshlrev_b32_e32 v90, 16, v62
	v_lshlrev_b32_e32 v91, 16, v58
	v_pk_fma_f32 v[72:73], v[136:137], v[98:99], v[72:73]
	v_lshlrev_b32_e32 v86, 16, v63
	v_pk_fma_f32 v[72:73], v[138:139], v[90:91], v[72:73]
	v_lshlrev_b32_e32 v87, 16, v59
	v_mul_f32_e32 v82, v73, v73
	v_fmamk_f32 v82, v82, 0xbdd2d3e7, v251
	v_mul_f32_e32 v82, v73, v82
	v_exp_f32_e32 v82, v82
	v_and_b32_e32 v59, 0xffff0000, v59
	v_lshlrev_b32_e32 v84, 16, v64
	v_lshlrev_b32_e32 v85, 16, v60
	v_add_f32_e32 v82, 1.0, v82
	v_rcp_f32_e32 v82, v82
	s_nop 0
	v_mul_f32_e32 v73, v73, v82
	v_pk_fma_f32 v[82:83], v[18:19], v[88:89], v[30:31]
	v_mul_f32_e32 v124, v72, v73
	v_and_b32_e32 v73, 0xffff0000, v58
	v_and_b32_e32 v72, 0xffff0000, v62
	v_pk_fma_f32 v[82:83], v[22:23], v[80:81], v[82:83]
	s_nop 0
	v_pk_fma_f32 v[82:83], v[26:27], v[72:73], v[82:83]
	s_nop 0
	v_mul_f32_e32 v58, v83, v83
	v_fmamk_f32 v58, v58, 0xbdd2d3e7, v251
	v_mul_f32_e32 v58, v83, v58
	v_exp_f32_e32 v58, v58
	s_nop 0
	v_add_f32_e32 v58, 1.0, v58
	v_rcp_f32_e32 v58, v58
	s_nop 0
	v_mul_f32_e32 v58, v83, v58
	v_mul_f32_e32 v88, v82, v58
	v_pk_fma_f32 v[82:83], v[106:107], v[104:105], v[110:111]
	s_nop 0
	v_pk_fma_f32 v[82:83], v[114:115], v[96:97], v[82:83]
	s_nop 0
	v_pk_fma_f32 v[82:83], v[118:119], v[86:87], v[82:83]
	s_nop 0
	v_mul_f32_e32 v58, v83, v83
	v_fmamk_f32 v58, v58, 0xbdd2d3e7, v251
	v_mul_f32_e32 v58, v83, v58
	v_exp_f32_e32 v58, v58
	s_nop 0
	v_add_f32_e32 v58, 1.0, v58
	v_rcp_f32_e32 v58, v58
	s_nop 0
	v_mul_f32_e32 v58, v83, v58
	v_mul_f32_e32 v89, v82, v58
	v_and_b32_e32 v58, 0xffff0000, v63
	v_pk_fma_f32 v[62:63], v[20:21], v[74:75], v[32:33]
	v_lshlrev_b32_e32 v82, 16, v65
	v_pk_fma_f32 v[62:63], v[24:25], v[66:67], v[62:63]
	v_lshlrev_b32_e32 v83, 16, v61
	v_pk_fma_f32 v[62:63], v[28:29], v[58:59], v[62:63]
	v_and_b32_e32 v61, 0xffff0000, v61
	v_mul_f32_e32 v74, v63, v63
	v_fmamk_f32 v74, v74, 0xbdd2d3e7, v251
	v_mul_f32_e32 v74, v63, v74
	v_exp_f32_e32 v74, v74
	s_nop 0
	v_add_f32_e32 v74, 1.0, v74
	v_rcp_f32_e32 v74, v74
	s_nop 0
	v_mul_f32_e32 v63, v63, v74
	v_mul_f32_e32 v104, v62, v63
	v_pk_fma_f32 v[62:63], v[108:109], v[102:103], v[112:113]
	s_nop 0
	v_pk_fma_f32 v[62:63], v[116:117], v[94:95], v[62:63]
	s_nop 0
	v_pk_fma_f32 v[62:63], v[120:121], v[84:85], v[62:63]
	s_nop 0
	v_mul_f32_e32 v74, v63, v63
	v_fmamk_f32 v74, v74, 0xbdd2d3e7, v251
	v_mul_f32_e32 v74, v63, v74
	v_exp_f32_e32 v74, v74
	s_nop 0
	v_add_f32_e32 v74, 1.0, v74
	v_rcp_f32_e32 v74, v74
	s_nop 0
	v_mul_f32_e32 v63, v63, v74
	v_pk_fma_f32 v[74:75], v[2:3], v[78:79], v[14:15]
	v_mul_f32_e32 v102, v62, v63
	v_and_b32_e32 v63, 0xffff0000, v60
	v_and_b32_e32 v62, 0xffff0000, v64
	v_pk_fma_f32 v[74:75], v[6:7], v[70:71], v[74:75]
	s_nop 0
; __device__ __forceinline__ unsigned cvt_pk_bf16(float lo, float hi) { unsigned r; asm volatile("v_cvt_pk_bf16_f32 %0, %1, %2" : "=v"(r) : "v"(lo), "v"(hi)); return r; }
; __device__ __forceinline__ float gelu_tanh(float x) {
;     const float y = 0.7978845608028654f * (x + 0.044715f * x * x * x);
;     return x * __builtin_amdgcn_rcpf(1.0f + __builtin_amdgcn_exp2f(-2.0f * LOG2E * y));
; }
; __device__ __forceinline__ void phase_conv(const Params& p, int layer) {
;     ...
;         for (int rb = 0; rb < RCH; rb += 8) {
;             u32x4 gr[8], ur[8];
; #pragma unroll
;             for (int k = 0; k < 8; ++k) { gr[k] = __builtin_nontemporal_load((const u32x4*)(U + (size_t)(r0 + rb + k) * DFF2 + c)); ur[k] = __builtin_nontemporal_load((const u32x4*)(U + (size_t)(r0 + rb + k) * DFF2 + DFF + c)); }
; #pragma unroll
;             for (int k = 0; k < 8; ++k) {
;                 float g0[8], u0[8]; unpack8(gr[k], g0); unpack8(ur[k], u0);
;                 float o[8];
; #pragma unroll
;                 for (int e = 0; e < 8; ++e) {
;                     const float gp = bg[e] + wg[0][e] * g2[e] + wg[1][e] * g1[e] + wg[2][e] * g0[e];
;                     const float up = bu[e] + wu[0][e] * u2[e] + wu[1][e] * u1[e] + wu[2][e] * u0[e];
;                     o[e] = gelu_tanh(gp) * up;
;                     g2[e] = g1[e]; g1[e] = g0[e]; u2[e] = u1[e]; u1[e] = u0[e];
;                 }
;                 u32x4 w; w.x = cvt_pk_bf16(o[0], o[1]); w.y = cvt_pk_bf16(o[2], o[3]); w.z = cvt_pk_bf16(o[4], o[5]); w.w = cvt_pk_bf16(o[6], o[7]);
;                 *(u32x4*)(Gd + (size_t)(r0 + rb + k) * DFF + c) = w;
;             }
;         }
	v_pk_fma_f32 v[74:75], v[10:11], v[62:63], v[74:75]
	s_nop 0
	v_mul_f32_e32 v60, v75, v75
	v_fmamk_f32 v60, v60, 0xbdd2d3e7, v251
	v_mul_f32_e32 v60, v75, v60
	v_exp_f32_e32 v60, v60
	s_nop 0
	v_add_f32_e32 v60, 1.0, v60
	v_rcp_f32_e32 v60, v60
	s_nop 0
	v_mul_f32_e32 v60, v75, v60
	v_mul_f32_e32 v78, v74, v60
	v_pk_fma_f32 v[74:75], v[122:123], v[100:101], v[126:127]
	s_nop 0
	v_pk_fma_f32 v[74:75], v[140:141], v[92:93], v[74:75]
	s_nop 0
	v_pk_fma_f32 v[74:75], v[142:143], v[82:83], v[74:75]
	s_nop 0
	v_mul_f32_e32 v60, v75, v75
	v_fmamk_f32 v60, v60, 0xbdd2d3e7, v251
	v_mul_f32_e32 v60, v75, v60
	v_exp_f32_e32 v60, v60
	s_nop 0
	v_add_f32_e32 v60, 1.0, v60
	v_rcp_f32_e32 v60, v60
	s_nop 0
	v_mul_f32_e32 v60, v75, v60
	v_mul_f32_e32 v79, v74, v60
	v_and_b32_e32 v60, 0xffff0000, v65
	v_pk_fma_f32 v[64:65], v[4:5], v[76:77], v[16:17]
	s_nop 0
	v_pk_fma_f32 v[64:65], v[8:9], v[68:69], v[64:65]
	s_nop 0
	v_pk_fma_f32 v[64:65], v[12:13], v[60:61], v[64:65]
	s_nop 0
	v_mul_f32_e32 v74, v65, v65
	v_fmamk_f32 v74, v74, 0xbdd2d3e7, v251
	v_mul_f32_e32 v74, v65, v74
	v_exp_f32_e32 v74, v74
	s_nop 0
	v_add_f32_e32 v74, 1.0, v74
	v_rcp_f32_e32 v74, v74
	s_nop 0
	v_mul_f32_e32 v65, v65, v74
	v_mul_f32_e32 v64, v64, v65
	v_cvt_pk_bf16_f32 v74, v124, v88
	v_cvt_pk_bf16_f32 v75, v89, v104
	v_cvt_pk_bf16_f32 v76, v102, v78
	v_cvt_pk_bf16_f32 v77, v79, v64
	v_mad_i64_i32 v[64:65], s[2:3], v171, s12, v[130:131]
	global_store_dwordx4 v[64:65], v[74:77], off
	v_pk_fma_f32 v[64:65], v[132:133], v[98:99], v[134:135]
	s_waitcnt vmcnt(9)
	v_lshlrev_b32_e32 v78, 16, v54
	v_lshlrev_b32_e32 v79, 16, v50
	v_pk_fma_f32 v[64:65], v[136:137], v[90:91], v[64:65]
	v_lshlrev_b32_e32 v76, 16, v55
	v_pk_fma_f32 v[64:65], v[138:139], v[78:79], v[64:65]
	v_lshlrev_b32_e32 v77, 16, v51
	v_mul_f32_e32 v74, v65, v65
	v_fmamk_f32 v74, v74, 0xbdd2d3e7, v251
	v_mul_f32_e32 v74, v65, v74
	v_exp_f32_e32 v74, v74
	v_and_b32_e32 v51, 0xffff0000, v51
	v_add_f32_e32 v74, 1.0, v74
	v_rcp_f32_e32 v74, v74
	s_nop 0
	v_mul_f32_e32 v65, v65, v74
	v_pk_fma_f32 v[74:75], v[18:19], v[80:81], v[30:31]
	v_mul_f32_e32 v88, v64, v65
	v_and_b32_e32 v65, 0xffff0000, v50
	v_and_b32_e32 v64, 0xffff0000, v54
	v_pk_fma_f32 v[74:75], v[22:23], v[72:73], v[74:75]
	s_nop 0
	v_pk_fma_f32 v[74:75], v[26:27], v[64:65], v[74:75]
	s_nop 0
	v_mul_f32_e32 v50, v75, v75
	v_fmamk_f32 v50, v50, 0xbdd2d3e7, v251
	v_mul_f32_e32 v50, v75, v50
	v_exp_f32_e32 v50, v50
	s_nop 0
	v_add_f32_e32 v50, 1.0, v50
	v_rcp_f32_e32 v50, v50
	s_nop 0
	v_mul_f32_e32 v50, v75, v50
	v_mul_f32_e32 v80, v74, v50
	v_pk_fma_f32 v[74:75], v[106:107], v[96:97], v[110:111]
	s_nop 0
	v_pk_fma_f32 v[74:75], v[114:115], v[86:87], v[74:75]
	s_nop 0
	v_pk_fma_f32 v[74:75], v[118:119], v[76:77], v[74:75]
	s_nop 0
	v_mul_f32_e32 v50, v75, v75
	v_fmamk_f32 v50, v50, 0xbdd2d3e7, v251
	v_mul_f32_e32 v50, v75, v50
	v_exp_f32_e32 v50, v50
	s_nop 0
	v_add_f32_e32 v50, 1.0, v50
	v_rcp_f32_e32 v50, v50
	s_nop 0
	v_mul_f32_e32 v50, v75, v50
	v_mul_f32_e32 v81, v74, v50
	v_and_b32_e32 v50, 0xffff0000, v55
	v_pk_fma_f32 v[54:55], v[20:21], v[66:67], v[32:33]
	v_lshlrev_b32_e32 v74, 16, v56
	v_pk_fma_f32 v[54:55], v[24:25], v[58:59], v[54:55]
	v_lshlrev_b32_e32 v75, 16, v52
	v_pk_fma_f32 v[54:55], v[28:29], v[50:51], v[54:55]
	s_nop 0
	v_mul_f32_e32 v66, v55, v55
	v_fmamk_f32 v66, v66, 0xbdd2d3e7, v251
	v_mul_f32_e32 v66, v55, v66
	v_exp_f32_e32 v66, v66
	s_nop 0
	v_add_f32_e32 v66, 1.0, v66
	v_rcp_f32_e32 v66, v66
	s_nop 0
	v_mul_f32_e32 v55, v55, v66
	v_mul_f32_e32 v89, v54, v55
	v_pk_fma_f32 v[54:55], v[108:109], v[94:95], v[112:113]
	s_nop 0
	v_pk_fma_f32 v[54:55], v[116:117], v[84:85], v[54:55]
	s_nop 0
	v_pk_fma_f32 v[54:55], v[120:121], v[74:75], v[54:55]
	s_nop 0
	v_mul_f32_e32 v66, v55, v55
	v_fmamk_f32 v66, v66, 0xbdd2d3e7, v251
	v_mul_f32_e32 v66, v55, v66
	v_exp_f32_e32 v66, v66
	s_nop 0
	v_add_f32_e32 v66, 1.0, v66
	v_rcp_f32_e32 v66, v66
	s_nop 0
	v_mul_f32_e32 v55, v55, v66
	v_pk_fma_f32 v[66:67], v[2:3], v[70:71], v[14:15]
	v_mul_f32_e32 v94, v54, v55
	v_and_b32_e32 v55, 0xffff0000, v52
	v_and_b32_e32 v54, 0xffff0000, v56
	v_pk_fma_f32 v[66:67], v[6:7], v[62:63], v[66:67]
	v_pk_fma_f32 v[70:71], v[122:123], v[92:93], v[126:127]
	v_pk_fma_f32 v[66:67], v[10:11], v[54:55], v[66:67]
	v_pk_fma_f32 v[70:71], v[140:141], v[82:83], v[70:71]
	v_mul_f32_e32 v52, v67, v67
	v_fmamk_f32 v52, v52, 0xbdd2d3e7, v251
	v_mul_f32_e32 v52, v67, v52
	v_exp_f32_e32 v52, v52
	s_nop 0
	v_add_f32_e32 v52, 1.0, v52
	v_rcp_f32_e32 v52, v52
	s_nop 0
	v_mul_f32_e32 v52, v67, v52
	v_mul_f32_e32 v95, v66, v52
	v_lshlrev_b32_e32 v66, 16, v57
	v_lshlrev_b32_e32 v67, 16, v53
	v_pk_fma_f32 v[70:71], v[142:143], v[66:67], v[70:71]
	v_and_b32_e32 v53, 0xffff0000, v53
	v_mul_f32_e32 v52, v71, v71
	v_fmamk_f32 v52, v52, 0xbdd2d3e7, v251
	v_mul_f32_e32 v52, v71, v52
	v_exp_f32_e32 v52, v52
	s_nop 0
	v_add_f32_e32 v52, 1.0, v52
	v_rcp_f32_e32 v52, v52
	s_nop 0
	v_mul_f32_e32 v52, v71, v52
	v_mul_f32_e32 v71, v70, v52
	v_and_b32_e32 v52, 0xffff0000, v57
	v_pk_fma_f32 v[56:57], v[4:5], v[68:69], v[16:17]
	s_nop 0
	v_pk_fma_f32 v[56:57], v[8:9], v[60:61], v[56:57]
	s_nop 0
	v_pk_fma_f32 v[56:57], v[12:13], v[52:53], v[56:57]
	s_nop 0
	v_mul_f32_e32 v68, v57, v57
	v_fmamk_f32 v68, v68, 0xbdd2d3e7, v251
	v_mul_f32_e32 v68, v57, v68
	v_exp_f32_e32 v68, v68
	s_nop 0
	v_add_f32_e32 v68, 1.0, v68
	v_rcp_f32_e32 v68, v68
	s_nop 0
	v_mul_f32_e32 v57, v57, v68
	v_mul_f32_e32 v56, v56, v57
	v_cvt_pk_bf16_f32 v68, v88, v80
	v_cvt_pk_bf16_f32 v69, v81, v89
	v_cvt_pk_bf16_f32 v70, v94, v95
	v_cvt_pk_bf16_f32 v71, v71, v56
	v_mad_i64_i32 v[56:57], s[2:3], v170, s12, v[130:131]
	global_store_dwordx4 v[56:57], v[68:71], off
	v_pk_fma_f32 v[56:57], v[132:133], v[90:91], v[134:135]
	s_waitcnt vmcnt(8)
; __device__ __forceinline__ unsigned cvt_pk_bf16(float lo, float hi) { unsigned r; asm volatile("v_cvt_pk_bf16_f32 %0, %1, %2" : "=v"(r) : "v"(lo), "v"(hi)); return r; }
; __device__ __forceinline__ float gelu_tanh(float x) {
;     const float y = 0.7978845608028654f * (x + 0.044715f * x * x * x);
;     return x * __builtin_amdgcn_rcpf(1.0f + __builtin_amdgcn_exp2f(-2.0f * LOG2E * y));
; }
; __device__ __forceinline__ void phase_conv(const Params& p, int layer) {
;     ...
;         for (int rb = 0; rb < RCH; rb += 8) {
;             u32x4 gr[8], ur[8];
; #pragma unroll
;             for (int k = 0; k < 8; ++k) { gr[k] = __builtin_nontemporal_load((const u32x4*)(U + (size_t)(r0 + rb + k) * DFF2 + c)); ur[k] = __builtin_nontemporal_load((const u32x4*)(U + (size_t)(r0 + rb + k) * DFF2 + DFF + c)); }
; #pragma unroll
;             for (int k = 0; k < 8; ++k) {
;                 float g0[8], u0[8]; unpack8(gr[k], g0); unpack8(ur[k], u0);
;                 float o[8];
; #pragma unroll
;                 for (int e = 0; e < 8; ++e) {
;                     const float gp = bg[e] + wg[0][e] * g2[e] + wg[1][e] * g1[e] + wg[2][e] * g0[e];
;                     const float up = bu[e] + wu[0][e] * u2[e] + wu[1][e] * u1[e] + wu[2][e] * u0[e];
;                     o[e] = gelu_tanh(gp) * up;
;                     g2[e] = g1[e]; g1[e] = g0[e]; u2[e] = u1[e]; u1[e] = u0[e];
;                 }
;                 u32x4 w; w.x = cvt_pk_bf16(o[0], o[1]); w.y = cvt_pk_bf16(o[2], o[3]); w.z = cvt_pk_bf16(o[4], o[5]); w.w = cvt_pk_bf16(o[6], o[7]);
;                 *(u32x4*)(Gd + (size_t)(r0 + rb + k) * DFF + c) = w;
;             }
;         }
	v_lshlrev_b32_e32 v80, 16, v46
	v_lshlrev_b32_e32 v81, 16, v42
	v_pk_fma_f32 v[56:57], v[136:137], v[78:79], v[56:57]
	v_lshlrev_b32_e32 v70, 16, v47
	v_pk_fma_f32 v[56:57], v[138:139], v[80:81], v[56:57]
	v_lshlrev_b32_e32 v71, 16, v43
	v_mul_f32_e32 v68, v57, v57
	v_fmamk_f32 v68, v68, 0xbdd2d3e7, v251
	v_mul_f32_e32 v68, v57, v68
	v_exp_f32_e32 v68, v68
	v_and_b32_e32 v43, 0xffff0000, v43
	v_add_f32_e32 v68, 1.0, v68
	v_rcp_f32_e32 v68, v68
	s_nop 0
	v_mul_f32_e32 v57, v57, v68
	v_pk_fma_f32 v[68:69], v[18:19], v[72:73], v[30:31]
	v_mul_f32_e32 v88, v56, v57
	v_and_b32_e32 v57, 0xffff0000, v42
	v_and_b32_e32 v56, 0xffff0000, v46
	v_pk_fma_f32 v[68:69], v[22:23], v[64:65], v[68:69]
	v_pk_fma_f32 v[18:19], v[18:19], v[64:65], v[30:31]
	v_pk_fma_f32 v[68:69], v[26:27], v[56:57], v[68:69]
	v_pk_fma_f32 v[18:19], v[22:23], v[56:57], v[18:19]
	v_mul_f32_e32 v42, v69, v69
	v_fmamk_f32 v42, v42, 0xbdd2d3e7, v251
	v_mul_f32_e32 v42, v69, v42
	v_exp_f32_e32 v42, v42
	s_nop 0
	v_add_f32_e32 v42, 1.0, v42
	v_rcp_f32_e32 v42, v42
	s_nop 0
	v_mul_f32_e32 v42, v69, v42
	v_mul_f32_e32 v72, v68, v42
	v_pk_fma_f32 v[68:69], v[106:107], v[86:87], v[110:111]
	s_nop 0
	v_pk_fma_f32 v[68:69], v[114:115], v[76:77], v[68:69]
	s_nop 0
	v_pk_fma_f32 v[68:69], v[118:119], v[70:71], v[68:69]
	s_nop 0
	v_mul_f32_e32 v42, v69, v69
	v_fmamk_f32 v42, v42, 0xbdd2d3e7, v251
	v_mul_f32_e32 v42, v69, v42
	v_exp_f32_e32 v42, v42
	s_nop 0
	v_add_f32_e32 v42, 1.0, v42
	v_rcp_f32_e32 v42, v42
	s_nop 0
	v_mul_f32_e32 v42, v69, v42
	v_mul_f32_e32 v73, v68, v42
	v_and_b32_e32 v42, 0xffff0000, v47
	v_pk_fma_f32 v[46:47], v[20:21], v[58:59], v[32:33]
	v_lshlrev_b32_e32 v68, 16, v48
	v_pk_fma_f32 v[46:47], v[24:25], v[50:51], v[46:47]
	v_lshlrev_b32_e32 v69, 16, v44
	v_pk_fma_f32 v[46:47], v[28:29], v[42:43], v[46:47]
	v_pk_fma_f32 v[20:21], v[20:21], v[50:51], v[32:33]
	v_mul_f32_e32 v58, v47, v47
	v_fmamk_f32 v58, v58, 0xbdd2d3e7, v251
	v_mul_f32_e32 v58, v47, v58
	v_exp_f32_e32 v58, v58
	v_pk_fma_f32 v[20:21], v[24:25], v[42:43], v[20:21]
	v_add_f32_e32 v58, 1.0, v58
	v_rcp_f32_e32 v58, v58
	s_nop 0
	v_mul_f32_e32 v47, v47, v58
	v_mul_f32_e32 v86, v46, v47
	v_pk_fma_f32 v[46:47], v[108:109], v[84:85], v[112:113]
	s_nop 0
	v_pk_fma_f32 v[46:47], v[116:117], v[74:75], v[46:47]
	s_nop 0
	v_pk_fma_f32 v[46:47], v[120:121], v[68:69], v[46:47]
	s_nop 0
	v_mul_f32_e32 v58, v47, v47
	v_fmamk_f32 v58, v58, 0xbdd2d3e7, v251
	v_mul_f32_e32 v58, v47, v58
	v_exp_f32_e32 v58, v58
	s_nop 0
	v_add_f32_e32 v58, 1.0, v58
	v_rcp_f32_e32 v58, v58
	s_nop 0
	v_mul_f32_e32 v47, v47, v58
	v_pk_fma_f32 v[58:59], v[2:3], v[62:63], v[14:15]
	v_mul_f32_e32 v84, v46, v47
	v_and_b32_e32 v47, 0xffff0000, v44
	v_and_b32_e32 v46, 0xffff0000, v48
	v_pk_fma_f32 v[58:59], v[6:7], v[54:55], v[58:59]
	v_pk_fma_f32 v[62:63], v[122:123], v[82:83], v[126:127]
	v_pk_fma_f32 v[58:59], v[10:11], v[46:47], v[58:59]
	v_pk_fma_f32 v[62:63], v[140:141], v[66:67], v[62:63]
	v_mul_f32_e32 v44, v59, v59
	v_fmamk_f32 v44, v44, 0xbdd2d3e7, v251
	v_mul_f32_e32 v44, v59, v44
	v_exp_f32_e32 v44, v44
	v_pk_fma_f32 v[2:3], v[2:3], v[54:55], v[14:15]
	v_add_f32_e32 v44, 1.0, v44
	v_rcp_f32_e32 v44, v44
	v_pk_fma_f32 v[2:3], v[6:7], v[46:47], v[2:3]
	v_mul_f32_e32 v44, v59, v44
	v_mul_f32_e32 v85, v58, v44
	v_lshlrev_b32_e32 v58, 16, v49
	v_lshlrev_b32_e32 v59, 16, v45
	v_pk_fma_f32 v[62:63], v[142:143], v[58:59], v[62:63]
	v_and_b32_e32 v45, 0xffff0000, v45
	v_mul_f32_e32 v44, v63, v63
	v_fmamk_f32 v44, v44, 0xbdd2d3e7, v251
	v_mul_f32_e32 v44, v63, v44
	v_exp_f32_e32 v44, v44
	s_nop 0
	v_add_f32_e32 v44, 1.0, v44
	v_rcp_f32_e32 v44, v44
	s_nop 0
	v_mul_f32_e32 v44, v63, v44
	v_mul_f32_e32 v63, v62, v44
	v_and_b32_e32 v44, 0xffff0000, v49
	v_pk_fma_f32 v[48:49], v[4:5], v[60:61], v[16:17]
	v_pk_fma_f32 v[4:5], v[4:5], v[52:53], v[16:17]
	v_pk_fma_f32 v[48:49], v[8:9], v[52:53], v[48:49]
	v_pk_fma_f32 v[4:5], v[8:9], v[44:45], v[4:5]
	v_pk_fma_f32 v[48:49], v[12:13], v[44:45], v[48:49]
	s_nop 0
	v_mul_f32_e32 v60, v49, v49
	v_fmamk_f32 v60, v60, 0xbdd2d3e7, v251
	v_mul_f32_e32 v60, v49, v60
	v_exp_f32_e32 v60, v60
	s_nop 0
	v_add_f32_e32 v60, 1.0, v60
	v_rcp_f32_e32 v60, v60
	s_nop 0
	v_mul_f32_e32 v49, v49, v60
	v_mul_f32_e32 v48, v48, v49
	v_cvt_pk_bf16_f32 v60, v88, v72
	v_cvt_pk_bf16_f32 v61, v73, v86
	v_cvt_pk_bf16_f32 v62, v84, v85
	v_cvt_pk_bf16_f32 v63, v63, v48
	v_mad_i64_i32 v[48:49], s[2:3], v169, s12, v[130:131]
	global_store_dwordx4 v[48:49], v[60:63], off
	s_waitcnt vmcnt(7)
; __device__ __forceinline__ unsigned cvt_pk_bf16(float lo, float hi) { unsigned r; asm volatile("v_cvt_pk_bf16_f32 %0, %1, %2" : "=v"(r) : "v"(lo), "v"(hi)); return r; }
; __device__ __forceinline__ float gelu_tanh(float x) {
;     const float y = 0.7978845608028654f * (x + 0.044715f * x * x * x);
;     return x * __builtin_amdgcn_rcpf(1.0f + __builtin_amdgcn_exp2f(-2.0f * LOG2E * y));
; }
; __device__ __forceinline__ void phase_conv(const Params& p, int layer) {
;     ...
;     for (int task = gtid; task < NCV * NCH; task += nthr) {
;     ...
;         for (int rb = 0; rb < RCH; rb += 8) {
;             u32x4 gr[8], ur[8];
; #pragma unroll
;             for (int k = 0; k < 8; ++k) { gr[k] = __builtin_nontemporal_load((const u32x4*)(U + (size_t)(r0 + rb + k) * DFF2 + c)); ur[k] = __builtin_nontemporal_load((const u32x4*)(U + (size_t)(r0 + rb + k) * DFF2 + DFF + c)); }
; #pragma unroll
;             for (int k = 0; k < 8; ++k) {
;                 float g0[8], u0[8]; unpack8(gr[k], g0); unpack8(ur[k], u0);
;                 float o[8];
; #pragma unroll
;                 for (int e = 0; e < 8; ++e) {
;                     const float gp = bg[e] + wg[0][e] * g2[e] + wg[1][e] * g1[e] + wg[2][e] * g0[e];
;                     const float up = bu[e] + wu[0][e] * u2[e] + wu[1][e] * u1[e] + wu[2][e] * u0[e];
;                     o[e] = gelu_tanh(gp) * up;
;                     g2[e] = g1[e]; g1[e] = g0[e]; u2[e] = u1[e]; u1[e] = u0[e];
;                 }
;                 u32x4 w; w.x = cvt_pk_bf16(o[0], o[1]); w.y = cvt_pk_bf16(o[2], o[3]); w.z = cvt_pk_bf16(o[4], o[5]); w.w = cvt_pk_bf16(o[6], o[7]);
;                 *(u32x4*)(Gd + (size_t)(r0 + rb + k) * DFF + c) = w;
;             }
;         }
	v_lshlrev_b32_e32 v48, 16, v38
	v_lshlrev_b32_e32 v49, 16, v34
	v_pk_fma_f32 v[60:61], v[132:133], v[78:79], v[134:135]
	s_nop 0
	v_pk_fma_f32 v[60:61], v[136:137], v[80:81], v[60:61]
	s_nop 0
	v_pk_fma_f32 v[48:49], v[138:139], v[48:49], v[60:61]
	s_nop 0
	v_mul_f32_e32 v60, v49, v49
	v_fmamk_f32 v60, v60, 0xbdd2d3e7, v251
	v_mul_f32_e32 v60, v49, v60
	v_exp_f32_e32 v60, v60
	s_nop 0
	v_add_f32_e32 v60, 1.0, v60
	v_rcp_f32_e32 v60, v60
	s_nop 0
	v_mul_f32_e32 v49, v49, v60
	v_mul_f32_e32 v60, v48, v49
	v_and_b32_e32 v49, 0xffff0000, v34
	v_and_b32_e32 v48, 0xffff0000, v38
	v_pk_fma_f32 v[18:19], v[26:27], v[48:49], v[18:19]
	s_nop 0
	v_mul_f32_e32 v22, v19, v19
	v_fmamk_f32 v22, v22, 0xbdd2d3e7, v251
	v_mul_f32_e32 v22, v19, v22
	v_exp_f32_e32 v22, v22
	s_nop 0
	v_add_f32_e32 v22, 1.0, v22
	v_rcp_f32_e32 v22, v22
	s_nop 0
	v_mul_f32_e32 v19, v19, v22
	v_pk_fma_f32 v[22:23], v[106:107], v[76:77], v[110:111]
	v_mul_f32_e32 v26, v18, v19
	v_lshlrev_b32_e32 v18, 16, v39
	v_lshlrev_b32_e32 v19, 16, v35
	v_pk_fma_f32 v[22:23], v[114:115], v[70:71], v[22:23]
	s_nop 0
	v_pk_fma_f32 v[18:19], v[118:119], v[18:19], v[22:23]
	s_nop 0
	v_mul_f32_e32 v22, v19, v19
	v_fmamk_f32 v22, v22, 0xbdd2d3e7, v251
	v_mul_f32_e32 v22, v19, v22
	v_exp_f32_e32 v22, v22
	s_nop 0
	v_add_f32_e32 v22, 1.0, v22
	v_rcp_f32_e32 v22, v22
	s_nop 0
	v_mul_f32_e32 v19, v19, v22
	v_mul_f32_e32 v22, v18, v19
	v_and_b32_e32 v19, 0xffff0000, v35
	v_and_b32_e32 v18, 0xffff0000, v39
	v_pk_fma_f32 v[18:19], v[28:29], v[18:19], v[20:21]
	s_nop 0
	v_mul_f32_e32 v20, v19, v19
	v_fmamk_f32 v20, v20, 0xbdd2d3e7, v251
	v_mul_f32_e32 v20, v19, v20
	v_exp_f32_e32 v20, v20
	s_nop 0
	v_add_f32_e32 v20, 1.0, v20
	v_rcp_f32_e32 v20, v20
	s_nop 0
	v_mul_f32_e32 v19, v19, v20
	v_pk_fma_f32 v[20:21], v[108:109], v[74:75], v[112:113]
	v_mul_f32_e32 v23, v18, v19
	v_lshlrev_b32_e32 v18, 16, v40
	v_lshlrev_b32_e32 v19, 16, v36
	v_pk_fma_f32 v[20:21], v[116:117], v[68:69], v[20:21]
	s_nop 0
	v_pk_fma_f32 v[18:19], v[120:121], v[18:19], v[20:21]
	s_nop 0
	v_mul_f32_e32 v20, v19, v19
	v_fmamk_f32 v20, v20, 0xbdd2d3e7, v251
	v_mul_f32_e32 v20, v19, v20
	v_exp_f32_e32 v20, v20
	s_nop 0
	v_add_f32_e32 v20, 1.0, v20
	v_rcp_f32_e32 v20, v20
	s_nop 0
	v_mul_f32_e32 v19, v19, v20
	v_mul_f32_e32 v20, v18, v19
	v_and_b32_e32 v19, 0xffff0000, v36
	v_and_b32_e32 v18, 0xffff0000, v40
	v_pk_fma_f32 v[2:3], v[10:11], v[18:19], v[2:3]
	s_nop 0
	v_mul_f32_e32 v6, v3, v3
	v_fmamk_f32 v6, v6, 0xbdd2d3e7, v251
	v_mul_f32_e32 v6, v3, v6
	v_exp_f32_e32 v6, v6
	s_nop 0
	v_add_f32_e32 v6, 1.0, v6
	v_rcp_f32_e32 v6, v6
	s_nop 0
	v_mul_f32_e32 v3, v3, v6
	v_pk_fma_f32 v[6:7], v[122:123], v[66:67], v[126:127]
	v_mul_f32_e32 v10, v2, v3
	v_lshlrev_b32_e32 v2, 16, v41
	v_lshlrev_b32_e32 v3, 16, v37
	v_pk_fma_f32 v[6:7], v[140:141], v[58:59], v[6:7]
	s_nop 0
	v_pk_fma_f32 v[2:3], v[142:143], v[2:3], v[6:7]
	s_nop 0
	v_mul_f32_e32 v6, v3, v3
	v_fmamk_f32 v6, v6, 0xbdd2d3e7, v251
	v_mul_f32_e32 v6, v3, v6
	v_exp_f32_e32 v6, v6
	s_nop 0
	v_add_f32_e32 v6, 1.0, v6
	v_rcp_f32_e32 v6, v6
	s_nop 0
	v_mul_f32_e32 v3, v3, v6
	v_mul_f32_e32 v6, v2, v3
	v_and_b32_e32 v3, 0xffff0000, v37
	v_and_b32_e32 v2, 0xffff0000, v41
	v_pk_fma_f32 v[2:3], v[12:13], v[2:3], v[4:5]
	s_nop 0
	v_mul_f32_e32 v4, v3, v3
	v_fmamk_f32 v4, v4, 0xbdd2d3e7, v251
	v_mul_f32_e32 v4, v3, v4
	v_exp_f32_e32 v4, v4
	s_nop 0
	v_add_f32_e32 v4, 1.0, v4
	v_rcp_f32_e32 v4, v4
	s_nop 0
	v_mul_f32_e32 v3, v3, v4
	v_mul_f32_e32 v5, v2, v3
	v_cvt_pk_bf16_f32 v2, v60, v26
	v_cvt_pk_bf16_f32 v3, v22, v23
	v_cvt_pk_bf16_f32 v4, v20, v10
	v_cvt_pk_bf16_f32 v5, v6, v5
	v_mad_i64_i32 v[6:7], s[2:3], v168, s12, v[130:131]
	s_mov_b32 s2, 0x5abff
	s_nop 0
	v_cmp_lt_i32_e32 vcc, s2, v0
	s_or_b64 s[54:55], vcc, s[54:55]
	global_store_dwordx4 v[6:7], v[2:5], off
	s_andn2_b64 exec, exec, s[54:55]
	s_cbranch_execz .LBB0_389
